# P1: workgroups with odd jblk run the CV block before the norm pass, others after (norm traffic and CV compute overlap across CUs)
# baseline (speedup 1.0000x reference)
.LBB0_438:
	s_mov_b32 s93, 0
	v_readlane_b32 s0, v254, 20
	s_bitcmp1_b32 s0, 3
	s_cbranch_scc0 .Lp1_norm
	s_mov_b32 s93, 1
	s_branch .LBB0_443

.Lp1_normdone:
	s_cmp_eq_u32 s93, 2
	s_cbranch_scc0 .LBB0_443
	s_waitcnt vmcnt(0)
	v_readlane_b32 s0, v254, 8
	v_readlane_b32 s1, v254, 9
	v_readlane_b32 s2, v254, 20
	v_mov_b32_e32 v15, 0
	v_mov_b32_e32 v11, 1
	s_and_b32 s3, s2, 7
	s_lshl_b32 s8, s3, 8
	s_add_u32 s8, s0, s8
	s_addc_u32 s9, s1, 0
	s_mov_b64 exec, 1
	global_atomic_add v15, v11, s[8:9] offset:2112
	s_mov_b64 exec, -1
	s_branch .LBB0_477
.LBB0_443:
	v_readlane_b32 s0, v254, 8
	v_readlane_b32 s1, v254, 9
	v_readlane_b32 s2, v254, 20
	v_mbcnt_lo_u32_b32 v0, -1, 0
	v_mbcnt_hi_u32_b32 v0, -1, v0
	s_and_b32 s3, s2, 7
	s_lshl_b32 s5, s2, 3
	s_add_i32 s5, s5, s69
	v_lshlrev_b32_e32 v1, 5, v0
	v_lshlrev_b32_e32 v4, 6, v0
	s_cmpk_lt_u32 s5, 0x7c0
	s_cbranch_scc0 .Lcv7_idle
	s_add_i32 s8, s5, 0xfffffdc0
	s_mov_b32 s10, 0x2100000
	s_mov_b32 s11, 0x3200000
	s_mov_b32 s22, 0x3e00000
	s_mov_b32 s23, 0x3d00000
	s_movk_i32 s83, 0x1600
	s_movk_i32 s84, 0x900
	s_movk_i32 s4, 0x6000
	s_movk_i32 s9, 0x3000
	s_cmpk_lt_u32 s5, 0x240
	s_cselect_b32 s8, s5, s8
	s_cselect_b32 s10, s11, s10
	s_cselect_b32 s22, s23, s22
	s_cselect_b32 s23, s84, s83
	s_cselect_b32 s4, s9, s4
	s_lshl_b32 s82, s8, 2
	s_lshl_b32 s8, s8, 13
	s_add_u32 s80, s0, s10
	s_addc_u32 s81, s1, 0
	s_add_u32 s80, s80, s8
	s_addc_u32 s81, s81, 0
	global_load_dwordx4 v[162:165], v1, s[80:81]
	global_load_dwordx4 v[166:169], v1, s[80:81] offset:16
	global_load_dwordx4 v[170:173], v1, s[80:81] offset:2048
	global_load_dwordx4 v[174:177], v1, s[80:81] offset:2064
	s_add_u32 s80, s80, 0x1000
	s_addc_u32 s81, s81, 0
	global_load_dwordx4 v[178:181], v1, s[80:81]
	global_load_dwordx4 v[182:185], v1, s[80:81] offset:16
	global_load_dwordx4 v[186:189], v1, s[80:81] offset:2048
	global_load_dwordx4 v[190:193], v1, s[80:81] offset:2064
	s_add_u32 s10, s0, 0x100000
	s_addc_u32 s11, s1, 0
	s_add_u32 s10, s10, s4
	s_addc_u32 s11, s11, 0
	global_load_dwordx4 v[194:197], v4, s[10:11]
	global_load_dwordx4 v[198:201], v4, s[10:11] offset:16
	global_load_dwordx4 v[202:205], v4, s[10:11] offset:32
	global_load_dwordx4 v[206:209], v4, s[10:11] offset:48
	s_add_u32 s10, s10, 0x9000
	s_addc_u32 s11, s11, 0
	global_load_dwordx4 v[226:229], v4, s[10:11]
	global_load_dwordx4 v[230:233], v4, s[10:11] offset:16
	global_load_dwordx4 v[234:237], v4, s[10:11] offset:32
	global_load_dwordx4 v[238:241], v4, s[10:11] offset:48
	s_add_u32 s10, s10, 0x9000
	s_addc_u32 s11, s11, 0
	s_waitcnt vmcnt(8)
	s_cmp_lg_u32 s93, 0
	s_cbranch_scc1 .Lcv8_noarr
	s_lshl_b32 s8, s3, 8
	s_add_u32 s8, s0, s8
	s_addc_u32 s9, s1, 0
	v_mov_b32_e32 v15, 0
	v_mov_b32_e32 v11, 1
	s_mov_b64 exec, 1
	global_atomic_add v15, v11, s[8:9] offset:2112
	s_mov_b64 exec, -1
.Lcv8_noarr:
	v_lshlrev_b32_e32 v28, 16, v162
	v_and_b32_e32 v29, 0xffff0000, v162
	v_lshlrev_b32_e32 v30, 16, v163
	v_and_b32_e32 v31, 0xffff0000, v163
	v_lshlrev_b32_e32 v32, 16, v164
	v_and_b32_e32 v33, 0xffff0000, v164
	v_lshlrev_b32_e32 v34, 16, v165
	v_and_b32_e32 v35, 0xffff0000, v165
	v_lshlrev_b32_e32 v36, 16, v166
	v_and_b32_e32 v37, 0xffff0000, v166
	v_lshlrev_b32_e32 v38, 16, v167
	v_and_b32_e32 v39, 0xffff0000, v167
	v_lshlrev_b32_e32 v40, 16, v168
	v_and_b32_e32 v41, 0xffff0000, v168
	v_lshlrev_b32_e32 v42, 16, v169
	v_and_b32_e32 v43, 0xffff0000, v169
	v_lshlrev_b32_e32 v44, 16, v170
	v_and_b32_e32 v45, 0xffff0000, v170
	v_lshlrev_b32_e32 v46, 16, v171
	v_and_b32_e32 v47, 0xffff0000, v171
	v_lshlrev_b32_e32 v48, 16, v172
	v_and_b32_e32 v49, 0xffff0000, v172
	v_lshlrev_b32_e32 v50, 16, v173
	v_and_b32_e32 v51, 0xffff0000, v173
	v_lshlrev_b32_e32 v52, 16, v174
	v_and_b32_e32 v53, 0xffff0000, v174
	v_lshlrev_b32_e32 v54, 16, v175
	v_and_b32_e32 v55, 0xffff0000, v175
	v_lshlrev_b32_e32 v56, 16, v176
	v_and_b32_e32 v57, 0xffff0000, v176
	v_lshlrev_b32_e32 v58, 16, v177
	v_and_b32_e32 v59, 0xffff0000, v177
	v_lshlrev_b32_e32 v60, 16, v178
	v_and_b32_e32 v61, 0xffff0000, v178
	v_lshlrev_b32_e32 v62, 16, v179
	v_and_b32_e32 v63, 0xffff0000, v179
	v_lshlrev_b32_e32 v64, 16, v180
	v_and_b32_e32 v65, 0xffff0000, v180
	v_lshlrev_b32_e32 v211, 16, v181
	v_and_b32_e32 v212, 0xffff0000, v181
	v_lshlrev_b32_e32 v213, 16, v182
	v_and_b32_e32 v214, 0xffff0000, v182
	v_lshlrev_b32_e32 v215, 16, v183
	v_and_b32_e32 v216, 0xffff0000, v183
	v_lshlrev_b32_e32 v217, 16, v184
	v_and_b32_e32 v218, 0xffff0000, v184
	v_lshlrev_b32_e32 v219, 16, v185
	v_and_b32_e32 v220, 0xffff0000, v185
	v_lshlrev_b32_e32 v221, 16, v186
	v_and_b32_e32 v222, 0xffff0000, v186
	v_lshlrev_b32_e32 v223, 16, v187
	v_and_b32_e32 v224, 0xffff0000, v187
	v_lshlrev_b32_e32 v242, 16, v188
	v_and_b32_e32 v243, 0xffff0000, v188
	v_lshlrev_b32_e32 v244, 16, v189
	v_and_b32_e32 v245, 0xffff0000, v189
	v_lshlrev_b32_e32 v246, 16, v190
	v_and_b32_e32 v247, 0xffff0000, v190
	v_lshlrev_b32_e32 v248, 16, v191
	v_and_b32_e32 v249, 0xffff0000, v191
	v_lshlrev_b32_e32 v250, 16, v192
	v_and_b32_e32 v251, 0xffff0000, v192
	v_lshlrev_b32_e32 v252, 16, v193
	v_and_b32_e32 v253, 0xffff0000, v193
	global_load_dwordx4 v[162:165], v4, s[10:11]
	global_load_dwordx4 v[166:169], v4, s[10:11] offset:16
	global_load_dwordx4 v[170:173], v4, s[10:11] offset:32
	global_load_dwordx4 v[174:177], v4, s[10:11] offset:48
	s_add_u32 s10, s10, 0x9000
	s_addc_u32 s11, s11, 0
	global_load_dwordx4 v[178:181], v4, s[10:11]
	global_load_dwordx4 v[182:185], v4, s[10:11] offset:16
	global_load_dwordx4 v[186:189], v4, s[10:11] offset:32
	global_load_dwordx4 v[190:193], v4, s[10:11] offset:48
	s_add_u32 s10, s10, 0x9000
	s_addc_u32 s11, s11, 0
	s_waitcnt vmcnt(8)
	v_mul_f32_e32 v98, v194, v28
	v_mul_f32_e32 v99, v194, v44
	v_mul_f32_e32 v100, v194, v60
	v_mul_f32_e32 v101, v194, v221
	v_mul_f32_e32 v102, v226, v28
	v_mul_f32_e32 v103, v226, v44
	v_mul_f32_e32 v104, v226, v60
	v_mul_f32_e32 v105, v226, v221
	v_fmac_f32_e32 v98, v195, v29
	v_fmac_f32_e32 v99, v195, v45
	v_fmac_f32_e32 v100, v195, v61
	v_fmac_f32_e32 v101, v195, v222
	v_fmac_f32_e32 v102, v227, v29
	v_fmac_f32_e32 v103, v227, v45
	v_fmac_f32_e32 v104, v227, v61
	v_fmac_f32_e32 v105, v227, v222
	v_fmac_f32_e32 v98, v196, v30
	v_fmac_f32_e32 v99, v196, v46
	v_fmac_f32_e32 v100, v196, v62
	v_fmac_f32_e32 v101, v196, v223
	v_fmac_f32_e32 v102, v228, v30
	v_fmac_f32_e32 v103, v228, v46
	v_fmac_f32_e32 v104, v228, v62
	v_fmac_f32_e32 v105, v228, v223
	v_fmac_f32_e32 v98, v197, v31
	v_fmac_f32_e32 v99, v197, v47
	v_fmac_f32_e32 v100, v197, v63
	v_fmac_f32_e32 v101, v197, v224
	v_fmac_f32_e32 v102, v229, v31
	v_fmac_f32_e32 v103, v229, v47
	v_fmac_f32_e32 v104, v229, v63
	v_fmac_f32_e32 v105, v229, v224
	v_fmac_f32_e32 v98, v198, v32
	v_fmac_f32_e32 v99, v198, v48
	v_fmac_f32_e32 v100, v198, v64
	v_fmac_f32_e32 v101, v198, v242
	v_fmac_f32_e32 v102, v230, v32
	v_fmac_f32_e32 v103, v230, v48
	v_fmac_f32_e32 v104, v230, v64
	v_fmac_f32_e32 v105, v230, v242
	v_fmac_f32_e32 v98, v199, v33
	v_fmac_f32_e32 v99, v199, v49
	v_fmac_f32_e32 v100, v199, v65
	v_fmac_f32_e32 v101, v199, v243
	v_fmac_f32_e32 v102, v231, v33
	v_fmac_f32_e32 v103, v231, v49
	v_fmac_f32_e32 v104, v231, v65
	v_fmac_f32_e32 v105, v231, v243
	v_fmac_f32_e32 v98, v200, v34
	v_fmac_f32_e32 v99, v200, v50
	v_fmac_f32_e32 v100, v200, v211
	v_fmac_f32_e32 v101, v200, v244
	v_fmac_f32_e32 v102, v232, v34
	v_fmac_f32_e32 v103, v232, v50
	v_fmac_f32_e32 v104, v232, v211
	v_fmac_f32_e32 v105, v232, v244
	v_fmac_f32_e32 v98, v201, v35
	v_fmac_f32_e32 v99, v201, v51
	v_fmac_f32_e32 v100, v201, v212
	v_fmac_f32_e32 v101, v201, v245
	v_fmac_f32_e32 v102, v233, v35
	v_fmac_f32_e32 v103, v233, v51
	v_fmac_f32_e32 v104, v233, v212
	v_fmac_f32_e32 v105, v233, v245
	v_fmac_f32_e32 v98, v202, v36
	v_fmac_f32_e32 v99, v202, v52
	v_fmac_f32_e32 v100, v202, v213
	v_fmac_f32_e32 v101, v202, v246
	v_fmac_f32_e32 v102, v234, v36
	v_fmac_f32_e32 v103, v234, v52
	v_fmac_f32_e32 v104, v234, v213
	v_fmac_f32_e32 v105, v234, v246
	v_fmac_f32_e32 v98, v203, v37
	v_fmac_f32_e32 v99, v203, v53
	v_fmac_f32_e32 v100, v203, v214
	v_fmac_f32_e32 v101, v203, v247
	v_fmac_f32_e32 v102, v235, v37
	v_fmac_f32_e32 v103, v235, v53
	v_fmac_f32_e32 v104, v235, v214
	v_fmac_f32_e32 v105, v235, v247
	v_fmac_f32_e32 v98, v204, v38
	v_fmac_f32_e32 v99, v204, v54
	v_fmac_f32_e32 v100, v204, v215
	v_fmac_f32_e32 v101, v204, v248
	v_fmac_f32_e32 v102, v236, v38
	v_fmac_f32_e32 v103, v236, v54
	v_fmac_f32_e32 v104, v236, v215
	v_fmac_f32_e32 v105, v236, v248
	v_fmac_f32_e32 v98, v205, v39
	v_fmac_f32_e32 v99, v205, v55
	v_fmac_f32_e32 v100, v205, v216
	v_fmac_f32_e32 v101, v205, v249
	v_fmac_f32_e32 v102, v237, v39
	v_fmac_f32_e32 v103, v237, v55
	v_fmac_f32_e32 v104, v237, v216
	v_fmac_f32_e32 v105, v237, v249
	v_fmac_f32_e32 v98, v206, v40
	v_fmac_f32_e32 v99, v206, v56
	v_fmac_f32_e32 v100, v206, v217
	v_fmac_f32_e32 v101, v206, v250
	v_fmac_f32_e32 v102, v238, v40
	v_fmac_f32_e32 v103, v238, v56
	v_fmac_f32_e32 v104, v238, v217
	v_fmac_f32_e32 v105, v238, v250
	v_fmac_f32_e32 v98, v207, v41
	v_fmac_f32_e32 v99, v207, v57
	v_fmac_f32_e32 v100, v207, v218
	v_fmac_f32_e32 v101, v207, v251
	v_fmac_f32_e32 v102, v239, v41
	v_fmac_f32_e32 v103, v239, v57
	v_fmac_f32_e32 v104, v239, v218
	v_fmac_f32_e32 v105, v239, v251
	v_fmac_f32_e32 v98, v208, v42
	v_fmac_f32_e32 v99, v208, v58
	v_fmac_f32_e32 v100, v208, v219
	v_fmac_f32_e32 v101, v208, v252
	v_fmac_f32_e32 v102, v240, v42
	v_fmac_f32_e32 v103, v240, v58
	v_fmac_f32_e32 v104, v240, v219
	v_fmac_f32_e32 v105, v240, v252
	v_fmac_f32_e32 v98, v209, v43
	v_fmac_f32_e32 v99, v209, v59
	v_fmac_f32_e32 v100, v209, v220
	v_fmac_f32_e32 v101, v209, v253
	v_fmac_f32_e32 v102, v241, v43
	v_fmac_f32_e32 v103, v241, v59
	v_fmac_f32_e32 v104, v241, v220
	v_fmac_f32_e32 v105, v241, v253
	global_load_dwordx4 v[194:197], v4, s[10:11]
	global_load_dwordx4 v[198:201], v4, s[10:11] offset:16
	global_load_dwordx4 v[202:205], v4, s[10:11] offset:32
	global_load_dwordx4 v[206:209], v4, s[10:11] offset:48
	s_add_u32 s10, s10, 0x9000
	s_addc_u32 s11, s11, 0
	global_load_dwordx4 v[226:229], v4, s[10:11]
	global_load_dwordx4 v[230:233], v4, s[10:11] offset:16
	global_load_dwordx4 v[234:237], v4, s[10:11] offset:32
	global_load_dwordx4 v[238:241], v4, s[10:11] offset:48
	s_add_u32 s10, s10, 0x9000
	s_addc_u32 s11, s11, 0
	s_waitcnt vmcnt(8)
	v_mul_f32_e32 v106, v162, v28
	v_mul_f32_e32 v107, v162, v44
	v_mul_f32_e32 v108, v162, v60
	v_mul_f32_e32 v109, v162, v221
	v_mul_f32_e32 v110, v178, v28
	v_mul_f32_e32 v111, v178, v44
	v_mul_f32_e32 v112, v178, v60
	v_mul_f32_e32 v113, v178, v221
	v_fmac_f32_e32 v106, v163, v29
	v_fmac_f32_e32 v107, v163, v45
	v_fmac_f32_e32 v108, v163, v61
	v_fmac_f32_e32 v109, v163, v222
	v_fmac_f32_e32 v110, v179, v29
	v_fmac_f32_e32 v111, v179, v45
	v_fmac_f32_e32 v112, v179, v61
	v_fmac_f32_e32 v113, v179, v222
	v_fmac_f32_e32 v106, v164, v30
	v_fmac_f32_e32 v107, v164, v46
	v_fmac_f32_e32 v108, v164, v62
	v_fmac_f32_e32 v109, v164, v223
	v_fmac_f32_e32 v110, v180, v30
	v_fmac_f32_e32 v111, v180, v46
	v_fmac_f32_e32 v112, v180, v62
	v_fmac_f32_e32 v113, v180, v223
	v_fmac_f32_e32 v106, v165, v31
	v_fmac_f32_e32 v107, v165, v47
	v_fmac_f32_e32 v108, v165, v63
	v_fmac_f32_e32 v109, v165, v224
	v_fmac_f32_e32 v110, v181, v31
	v_fmac_f32_e32 v111, v181, v47
	v_fmac_f32_e32 v112, v181, v63
	v_fmac_f32_e32 v113, v181, v224
	v_fmac_f32_e32 v106, v166, v32
	v_fmac_f32_e32 v107, v166, v48
	v_fmac_f32_e32 v108, v166, v64
	v_fmac_f32_e32 v109, v166, v242
	v_fmac_f32_e32 v110, v182, v32
	v_fmac_f32_e32 v111, v182, v48
	v_fmac_f32_e32 v112, v182, v64
	v_fmac_f32_e32 v113, v182, v242
	v_fmac_f32_e32 v106, v167, v33
	v_fmac_f32_e32 v107, v167, v49
	v_fmac_f32_e32 v108, v167, v65
	v_fmac_f32_e32 v109, v167, v243
	v_fmac_f32_e32 v110, v183, v33
	v_fmac_f32_e32 v111, v183, v49
	v_fmac_f32_e32 v112, v183, v65
	v_fmac_f32_e32 v113, v183, v243
	v_fmac_f32_e32 v106, v168, v34
	v_fmac_f32_e32 v107, v168, v50
	v_fmac_f32_e32 v108, v168, v211
	v_fmac_f32_e32 v109, v168, v244
	v_fmac_f32_e32 v110, v184, v34
	v_fmac_f32_e32 v111, v184, v50
	v_fmac_f32_e32 v112, v184, v211
	v_fmac_f32_e32 v113, v184, v244
	v_fmac_f32_e32 v106, v169, v35
	v_fmac_f32_e32 v107, v169, v51
	v_fmac_f32_e32 v108, v169, v212
	v_fmac_f32_e32 v109, v169, v245
	v_fmac_f32_e32 v110, v185, v35
	v_fmac_f32_e32 v111, v185, v51
	v_fmac_f32_e32 v112, v185, v212
	v_fmac_f32_e32 v113, v185, v245
	v_fmac_f32_e32 v106, v170, v36
	v_fmac_f32_e32 v107, v170, v52
	v_fmac_f32_e32 v108, v170, v213
	v_fmac_f32_e32 v109, v170, v246
	v_fmac_f32_e32 v110, v186, v36
	v_fmac_f32_e32 v111, v186, v52
	v_fmac_f32_e32 v112, v186, v213
	v_fmac_f32_e32 v113, v186, v246
	v_fmac_f32_e32 v106, v171, v37
	v_fmac_f32_e32 v107, v171, v53
	v_fmac_f32_e32 v108, v171, v214
	v_fmac_f32_e32 v109, v171, v247
	v_fmac_f32_e32 v110, v187, v37
	v_fmac_f32_e32 v111, v187, v53
	v_fmac_f32_e32 v112, v187, v214
	v_fmac_f32_e32 v113, v187, v247
	v_fmac_f32_e32 v106, v172, v38
	v_fmac_f32_e32 v107, v172, v54
	v_fmac_f32_e32 v108, v172, v215
	v_fmac_f32_e32 v109, v172, v248
	v_fmac_f32_e32 v110, v188, v38
	v_fmac_f32_e32 v111, v188, v54
	v_fmac_f32_e32 v112, v188, v215
	v_fmac_f32_e32 v113, v188, v248
	v_fmac_f32_e32 v106, v173, v39
	v_fmac_f32_e32 v107, v173, v55
	v_fmac_f32_e32 v108, v173, v216
	v_fmac_f32_e32 v109, v173, v249
	v_fmac_f32_e32 v110, v189, v39
	v_fmac_f32_e32 v111, v189, v55
	v_fmac_f32_e32 v112, v189, v216
	v_fmac_f32_e32 v113, v189, v249
	v_fmac_f32_e32 v106, v174, v40
	v_fmac_f32_e32 v107, v174, v56
	v_fmac_f32_e32 v108, v174, v217
	v_fmac_f32_e32 v109, v174, v250
	v_fmac_f32_e32 v110, v190, v40
	v_fmac_f32_e32 v111, v190, v56
	v_fmac_f32_e32 v112, v190, v217
	v_fmac_f32_e32 v113, v190, v250
	v_fmac_f32_e32 v106, v175, v41
	v_fmac_f32_e32 v107, v175, v57
	v_fmac_f32_e32 v108, v175, v218
	v_fmac_f32_e32 v109, v175, v251
	v_fmac_f32_e32 v110, v191, v41
	v_fmac_f32_e32 v111, v191, v57
	v_fmac_f32_e32 v112, v191, v218
	v_fmac_f32_e32 v113, v191, v251
	v_fmac_f32_e32 v106, v176, v42
	v_fmac_f32_e32 v107, v176, v58
	v_fmac_f32_e32 v108, v176, v219
	v_fmac_f32_e32 v109, v176, v252
	v_fmac_f32_e32 v110, v192, v42
	v_fmac_f32_e32 v111, v192, v58
	v_fmac_f32_e32 v112, v192, v219
	v_fmac_f32_e32 v113, v192, v252
	v_fmac_f32_e32 v106, v177, v43
	v_fmac_f32_e32 v107, v177, v59
	v_fmac_f32_e32 v108, v177, v220
	v_fmac_f32_e32 v109, v177, v253
	v_fmac_f32_e32 v110, v193, v43
	v_fmac_f32_e32 v111, v193, v59
	v_fmac_f32_e32 v112, v193, v220
	v_fmac_f32_e32 v113, v193, v253
	global_load_dwordx4 v[162:165], v4, s[10:11]
	global_load_dwordx4 v[166:169], v4, s[10:11] offset:16
	global_load_dwordx4 v[170:173], v4, s[10:11] offset:32
	global_load_dwordx4 v[174:177], v4, s[10:11] offset:48
	s_add_u32 s10, s10, 0x9000
	s_addc_u32 s11, s11, 0
	global_load_dwordx4 v[178:181], v4, s[10:11]
	global_load_dwordx4 v[182:185], v4, s[10:11] offset:16
	global_load_dwordx4 v[186:189], v4, s[10:11] offset:32
	global_load_dwordx4 v[190:193], v4, s[10:11] offset:48
	s_add_u32 s10, s10, 0x9000
	s_addc_u32 s11, s11, 0
	s_waitcnt vmcnt(8)
	v_mul_f32_e32 v114, v194, v28
	v_mul_f32_e32 v115, v194, v44
	v_mul_f32_e32 v116, v194, v60
	v_mul_f32_e32 v117, v194, v221
	v_mul_f32_e32 v118, v226, v28
	v_mul_f32_e32 v119, v226, v44
	v_mul_f32_e32 v120, v226, v60
	v_mul_f32_e32 v121, v226, v221
	v_fmac_f32_e32 v114, v195, v29
	v_fmac_f32_e32 v115, v195, v45
	v_fmac_f32_e32 v116, v195, v61
	v_fmac_f32_e32 v117, v195, v222
	v_fmac_f32_e32 v118, v227, v29
	v_fmac_f32_e32 v119, v227, v45
	v_fmac_f32_e32 v120, v227, v61
	v_fmac_f32_e32 v121, v227, v222
	v_fmac_f32_e32 v114, v196, v30
	v_fmac_f32_e32 v115, v196, v46
	v_fmac_f32_e32 v116, v196, v62
	v_fmac_f32_e32 v117, v196, v223
	v_fmac_f32_e32 v118, v228, v30
	v_fmac_f32_e32 v119, v228, v46
	v_fmac_f32_e32 v120, v228, v62
	v_fmac_f32_e32 v121, v228, v223
	v_fmac_f32_e32 v114, v197, v31
	v_fmac_f32_e32 v115, v197, v47
	v_fmac_f32_e32 v116, v197, v63
	v_fmac_f32_e32 v117, v197, v224
	v_fmac_f32_e32 v118, v229, v31
	v_fmac_f32_e32 v119, v229, v47
	v_fmac_f32_e32 v120, v229, v63
	v_fmac_f32_e32 v121, v229, v224
	v_fmac_f32_e32 v114, v198, v32
	v_fmac_f32_e32 v115, v198, v48
	v_fmac_f32_e32 v116, v198, v64
	v_fmac_f32_e32 v117, v198, v242
	v_fmac_f32_e32 v118, v230, v32
	v_fmac_f32_e32 v119, v230, v48
	v_fmac_f32_e32 v120, v230, v64
	v_fmac_f32_e32 v121, v230, v242
	v_fmac_f32_e32 v114, v199, v33
	v_fmac_f32_e32 v115, v199, v49
	v_fmac_f32_e32 v116, v199, v65
	v_fmac_f32_e32 v117, v199, v243
	v_fmac_f32_e32 v118, v231, v33
	v_fmac_f32_e32 v119, v231, v49
	v_fmac_f32_e32 v120, v231, v65
	v_fmac_f32_e32 v121, v231, v243
	v_fmac_f32_e32 v114, v200, v34
	v_fmac_f32_e32 v115, v200, v50
	v_fmac_f32_e32 v116, v200, v211
	v_fmac_f32_e32 v117, v200, v244
	v_fmac_f32_e32 v118, v232, v34
	v_fmac_f32_e32 v119, v232, v50
	v_fmac_f32_e32 v120, v232, v211
	v_fmac_f32_e32 v121, v232, v244
	v_fmac_f32_e32 v114, v201, v35
	v_fmac_f32_e32 v115, v201, v51
	v_fmac_f32_e32 v116, v201, v212
	v_fmac_f32_e32 v117, v201, v245
	v_fmac_f32_e32 v118, v233, v35
	v_fmac_f32_e32 v119, v233, v51
	v_fmac_f32_e32 v120, v233, v212
	v_fmac_f32_e32 v121, v233, v245
	v_fmac_f32_e32 v114, v202, v36
	v_fmac_f32_e32 v115, v202, v52
	v_fmac_f32_e32 v116, v202, v213
	v_fmac_f32_e32 v117, v202, v246
	v_fmac_f32_e32 v118, v234, v36
	v_fmac_f32_e32 v119, v234, v52
	v_fmac_f32_e32 v120, v234, v213
	v_fmac_f32_e32 v121, v234, v246
	v_fmac_f32_e32 v114, v203, v37
	v_fmac_f32_e32 v115, v203, v53
	v_fmac_f32_e32 v116, v203, v214
	v_fmac_f32_e32 v117, v203, v247
	v_fmac_f32_e32 v118, v235, v37
	v_fmac_f32_e32 v119, v235, v53
	v_fmac_f32_e32 v120, v235, v214
	v_fmac_f32_e32 v121, v235, v247
	v_fmac_f32_e32 v114, v204, v38
	v_fmac_f32_e32 v115, v204, v54
	v_fmac_f32_e32 v116, v204, v215
	v_fmac_f32_e32 v117, v204, v248
	v_fmac_f32_e32 v118, v236, v38
	v_fmac_f32_e32 v119, v236, v54
	v_fmac_f32_e32 v120, v236, v215
	v_fmac_f32_e32 v121, v236, v248
	v_fmac_f32_e32 v114, v205, v39
	v_fmac_f32_e32 v115, v205, v55
	v_fmac_f32_e32 v116, v205, v216
	v_fmac_f32_e32 v117, v205, v249
	v_fmac_f32_e32 v118, v237, v39
	v_fmac_f32_e32 v119, v237, v55
	v_fmac_f32_e32 v120, v237, v216
	v_fmac_f32_e32 v121, v237, v249
	v_fmac_f32_e32 v114, v206, v40
	v_fmac_f32_e32 v115, v206, v56
	v_fmac_f32_e32 v116, v206, v217
	v_fmac_f32_e32 v117, v206, v250
	v_fmac_f32_e32 v118, v238, v40
	v_fmac_f32_e32 v119, v238, v56
	v_fmac_f32_e32 v120, v238, v217
	v_fmac_f32_e32 v121, v238, v250
	v_fmac_f32_e32 v114, v207, v41
	v_fmac_f32_e32 v115, v207, v57
	v_fmac_f32_e32 v116, v207, v218
	v_fmac_f32_e32 v117, v207, v251
	v_fmac_f32_e32 v118, v239, v41
	v_fmac_f32_e32 v119, v239, v57
	v_fmac_f32_e32 v120, v239, v218
	v_fmac_f32_e32 v121, v239, v251
	v_fmac_f32_e32 v114, v208, v42
	v_fmac_f32_e32 v115, v208, v58
	v_fmac_f32_e32 v116, v208, v219
	v_fmac_f32_e32 v117, v208, v252
	v_fmac_f32_e32 v118, v240, v42
	v_fmac_f32_e32 v119, v240, v58
	v_fmac_f32_e32 v120, v240, v219
	v_fmac_f32_e32 v121, v240, v252
	v_fmac_f32_e32 v114, v209, v43
	v_fmac_f32_e32 v115, v209, v59
	v_fmac_f32_e32 v116, v209, v220
	v_fmac_f32_e32 v117, v209, v253
	v_fmac_f32_e32 v118, v241, v43
	v_fmac_f32_e32 v119, v241, v59
	v_fmac_f32_e32 v120, v241, v220
	v_fmac_f32_e32 v121, v241, v253
	global_load_dwordx4 v[194:197], v4, s[10:11]
	global_load_dwordx4 v[198:201], v4, s[10:11] offset:16
	global_load_dwordx4 v[202:205], v4, s[10:11] offset:32
	global_load_dwordx4 v[206:209], v4, s[10:11] offset:48
	s_add_u32 s10, s10, 0x9000
	s_addc_u32 s11, s11, 0
	global_load_dwordx4 v[226:229], v4, s[10:11]
	global_load_dwordx4 v[230:233], v4, s[10:11] offset:16
	global_load_dwordx4 v[234:237], v4, s[10:11] offset:32
	global_load_dwordx4 v[238:241], v4, s[10:11] offset:48
	s_add_u32 s10, s10, 0x9000
	s_addc_u32 s11, s11, 0
	s_waitcnt vmcnt(8)
	v_mul_f32_e32 v122, v162, v28
	v_mul_f32_e32 v123, v162, v44
	v_mul_f32_e32 v124, v162, v60
	v_mul_f32_e32 v125, v162, v221
	v_mul_f32_e32 v126, v178, v28
	v_mul_f32_e32 v127, v178, v44
	v_mul_f32_e32 v128, v178, v60
	v_mul_f32_e32 v129, v178, v221
	v_fmac_f32_e32 v122, v163, v29
	v_fmac_f32_e32 v123, v163, v45
	v_fmac_f32_e32 v124, v163, v61
	v_fmac_f32_e32 v125, v163, v222
	v_fmac_f32_e32 v126, v179, v29
	v_fmac_f32_e32 v127, v179, v45
	v_fmac_f32_e32 v128, v179, v61
	v_fmac_f32_e32 v129, v179, v222
	v_fmac_f32_e32 v122, v164, v30
	v_fmac_f32_e32 v123, v164, v46
	v_fmac_f32_e32 v124, v164, v62
	v_fmac_f32_e32 v125, v164, v223
	v_fmac_f32_e32 v126, v180, v30
	v_fmac_f32_e32 v127, v180, v46
	v_fmac_f32_e32 v128, v180, v62
	v_fmac_f32_e32 v129, v180, v223
	v_fmac_f32_e32 v122, v165, v31
	v_fmac_f32_e32 v123, v165, v47
	v_fmac_f32_e32 v124, v165, v63
	v_fmac_f32_e32 v125, v165, v224
	v_fmac_f32_e32 v126, v181, v31
	v_fmac_f32_e32 v127, v181, v47
	v_fmac_f32_e32 v128, v181, v63
	v_fmac_f32_e32 v129, v181, v224
	v_fmac_f32_e32 v122, v166, v32
	v_fmac_f32_e32 v123, v166, v48
	v_fmac_f32_e32 v124, v166, v64
	v_fmac_f32_e32 v125, v166, v242
	v_fmac_f32_e32 v126, v182, v32
	v_fmac_f32_e32 v127, v182, v48
	v_fmac_f32_e32 v128, v182, v64
	v_fmac_f32_e32 v129, v182, v242
	v_fmac_f32_e32 v122, v167, v33
	v_fmac_f32_e32 v123, v167, v49
	v_fmac_f32_e32 v124, v167, v65
	v_fmac_f32_e32 v125, v167, v243
	v_fmac_f32_e32 v126, v183, v33
	v_fmac_f32_e32 v127, v183, v49
	v_fmac_f32_e32 v128, v183, v65
	v_fmac_f32_e32 v129, v183, v243
	v_fmac_f32_e32 v122, v168, v34
	v_fmac_f32_e32 v123, v168, v50
	v_fmac_f32_e32 v124, v168, v211
	v_fmac_f32_e32 v125, v168, v244
	v_fmac_f32_e32 v126, v184, v34
	v_fmac_f32_e32 v127, v184, v50
	v_fmac_f32_e32 v128, v184, v211
	v_fmac_f32_e32 v129, v184, v244
	v_fmac_f32_e32 v122, v169, v35
	v_fmac_f32_e32 v123, v169, v51
	v_fmac_f32_e32 v124, v169, v212
	v_fmac_f32_e32 v125, v169, v245
	v_fmac_f32_e32 v126, v185, v35
	v_fmac_f32_e32 v127, v185, v51
	v_fmac_f32_e32 v128, v185, v212
	v_fmac_f32_e32 v129, v185, v245
	v_fmac_f32_e32 v122, v170, v36
	v_fmac_f32_e32 v123, v170, v52
	v_fmac_f32_e32 v124, v170, v213
	v_fmac_f32_e32 v125, v170, v246
	v_fmac_f32_e32 v126, v186, v36
	v_fmac_f32_e32 v127, v186, v52
	v_fmac_f32_e32 v128, v186, v213
	v_fmac_f32_e32 v129, v186, v246
	v_fmac_f32_e32 v122, v171, v37
	v_fmac_f32_e32 v123, v171, v53
	v_fmac_f32_e32 v124, v171, v214
	v_fmac_f32_e32 v125, v171, v247
	v_fmac_f32_e32 v126, v187, v37
	v_fmac_f32_e32 v127, v187, v53
	v_fmac_f32_e32 v128, v187, v214
	v_fmac_f32_e32 v129, v187, v247
	v_fmac_f32_e32 v122, v172, v38
	v_fmac_f32_e32 v123, v172, v54
	v_fmac_f32_e32 v124, v172, v215
	v_fmac_f32_e32 v125, v172, v248
	v_fmac_f32_e32 v126, v188, v38
	v_fmac_f32_e32 v127, v188, v54
	v_fmac_f32_e32 v128, v188, v215
	v_fmac_f32_e32 v129, v188, v248
	v_fmac_f32_e32 v122, v173, v39
	v_fmac_f32_e32 v123, v173, v55
	v_fmac_f32_e32 v124, v173, v216
	v_fmac_f32_e32 v125, v173, v249
	v_fmac_f32_e32 v126, v189, v39
	v_fmac_f32_e32 v127, v189, v55
	v_fmac_f32_e32 v128, v189, v216
	v_fmac_f32_e32 v129, v189, v249
	v_fmac_f32_e32 v122, v174, v40
	v_fmac_f32_e32 v123, v174, v56
	v_fmac_f32_e32 v124, v174, v217
	v_fmac_f32_e32 v125, v174, v250
	v_fmac_f32_e32 v126, v190, v40
	v_fmac_f32_e32 v127, v190, v56
	v_fmac_f32_e32 v128, v190, v217
	v_fmac_f32_e32 v129, v190, v250
	v_fmac_f32_e32 v122, v175, v41
	v_fmac_f32_e32 v123, v175, v57
	v_fmac_f32_e32 v124, v175, v218
	v_fmac_f32_e32 v125, v175, v251
	v_fmac_f32_e32 v126, v191, v41
	v_fmac_f32_e32 v127, v191, v57
	v_fmac_f32_e32 v128, v191, v218
	v_fmac_f32_e32 v129, v191, v251
	v_fmac_f32_e32 v122, v176, v42
	v_fmac_f32_e32 v123, v176, v58
	v_fmac_f32_e32 v124, v176, v219
	v_fmac_f32_e32 v125, v176, v252
	v_fmac_f32_e32 v126, v192, v42
	v_fmac_f32_e32 v127, v192, v58
	v_fmac_f32_e32 v128, v192, v219
	v_fmac_f32_e32 v129, v192, v252
	v_fmac_f32_e32 v122, v177, v43
	v_fmac_f32_e32 v123, v177, v59
	v_fmac_f32_e32 v124, v177, v220
	v_fmac_f32_e32 v125, v177, v253
	v_fmac_f32_e32 v126, v193, v43
	v_fmac_f32_e32 v127, v193, v59
	v_fmac_f32_e32 v128, v193, v220
	v_fmac_f32_e32 v129, v193, v253
	global_load_dwordx4 v[162:165], v4, s[10:11]
	global_load_dwordx4 v[166:169], v4, s[10:11] offset:16
	global_load_dwordx4 v[170:173], v4, s[10:11] offset:32
	global_load_dwordx4 v[174:177], v4, s[10:11] offset:48
	s_add_u32 s10, s10, 0x9000
	s_addc_u32 s11, s11, 0
	global_load_dwordx4 v[178:181], v4, s[10:11]
	global_load_dwordx4 v[182:185], v4, s[10:11] offset:16
	global_load_dwordx4 v[186:189], v4, s[10:11] offset:32
	global_load_dwordx4 v[190:193], v4, s[10:11] offset:48
	s_add_u32 s10, s10, 0x9000
	s_addc_u32 s11, s11, 0
	s_waitcnt vmcnt(8)
	v_mul_f32_e32 v130, v194, v28
	v_mul_f32_e32 v131, v194, v44
	v_mul_f32_e32 v132, v194, v60
	v_mul_f32_e32 v133, v194, v221
	v_mul_f32_e32 v134, v226, v28
	v_mul_f32_e32 v135, v226, v44
	v_mul_f32_e32 v136, v226, v60
	v_mul_f32_e32 v137, v226, v221
	v_fmac_f32_e32 v130, v195, v29
	v_fmac_f32_e32 v131, v195, v45
	v_fmac_f32_e32 v132, v195, v61
	v_fmac_f32_e32 v133, v195, v222
	v_fmac_f32_e32 v134, v227, v29
	v_fmac_f32_e32 v135, v227, v45
	v_fmac_f32_e32 v136, v227, v61
	v_fmac_f32_e32 v137, v227, v222
	v_fmac_f32_e32 v130, v196, v30
	v_fmac_f32_e32 v131, v196, v46
	v_fmac_f32_e32 v132, v196, v62
	v_fmac_f32_e32 v133, v196, v223
	v_fmac_f32_e32 v134, v228, v30
	v_fmac_f32_e32 v135, v228, v46
	v_fmac_f32_e32 v136, v228, v62
	v_fmac_f32_e32 v137, v228, v223
	v_fmac_f32_e32 v130, v197, v31
	v_fmac_f32_e32 v131, v197, v47
	v_fmac_f32_e32 v132, v197, v63
	v_fmac_f32_e32 v133, v197, v224
	v_fmac_f32_e32 v134, v229, v31
	v_fmac_f32_e32 v135, v229, v47
	v_fmac_f32_e32 v136, v229, v63
	v_fmac_f32_e32 v137, v229, v224
	v_fmac_f32_e32 v130, v198, v32
	v_fmac_f32_e32 v131, v198, v48
	v_fmac_f32_e32 v132, v198, v64
	v_fmac_f32_e32 v133, v198, v242
	v_fmac_f32_e32 v134, v230, v32
	v_fmac_f32_e32 v135, v230, v48
	v_fmac_f32_e32 v136, v230, v64
	v_fmac_f32_e32 v137, v230, v242
	v_fmac_f32_e32 v130, v199, v33
	v_fmac_f32_e32 v131, v199, v49
	v_fmac_f32_e32 v132, v199, v65
	v_fmac_f32_e32 v133, v199, v243
	v_fmac_f32_e32 v134, v231, v33
	v_fmac_f32_e32 v135, v231, v49
	v_fmac_f32_e32 v136, v231, v65
	v_fmac_f32_e32 v137, v231, v243
	v_fmac_f32_e32 v130, v200, v34
	v_fmac_f32_e32 v131, v200, v50
	v_fmac_f32_e32 v132, v200, v211
	v_fmac_f32_e32 v133, v200, v244
	v_fmac_f32_e32 v134, v232, v34
	v_fmac_f32_e32 v135, v232, v50
	v_fmac_f32_e32 v136, v232, v211
	v_fmac_f32_e32 v137, v232, v244
	v_fmac_f32_e32 v130, v201, v35
	v_fmac_f32_e32 v131, v201, v51
	v_fmac_f32_e32 v132, v201, v212
	v_fmac_f32_e32 v133, v201, v245
	v_fmac_f32_e32 v134, v233, v35
	v_fmac_f32_e32 v135, v233, v51
	v_fmac_f32_e32 v136, v233, v212
	v_fmac_f32_e32 v137, v233, v245
	v_fmac_f32_e32 v130, v202, v36
	v_fmac_f32_e32 v131, v202, v52
	v_fmac_f32_e32 v132, v202, v213
	v_fmac_f32_e32 v133, v202, v246
	v_fmac_f32_e32 v134, v234, v36
	v_fmac_f32_e32 v135, v234, v52
	v_fmac_f32_e32 v136, v234, v213
	v_fmac_f32_e32 v137, v234, v246
	v_fmac_f32_e32 v130, v203, v37
	v_fmac_f32_e32 v131, v203, v53
	v_fmac_f32_e32 v132, v203, v214
	v_fmac_f32_e32 v133, v203, v247
	v_fmac_f32_e32 v134, v235, v37
	v_fmac_f32_e32 v135, v235, v53
	v_fmac_f32_e32 v136, v235, v214
	v_fmac_f32_e32 v137, v235, v247
	v_fmac_f32_e32 v130, v204, v38
	v_fmac_f32_e32 v131, v204, v54
	v_fmac_f32_e32 v132, v204, v215
	v_fmac_f32_e32 v133, v204, v248
	v_fmac_f32_e32 v134, v236, v38
	v_fmac_f32_e32 v135, v236, v54
	v_fmac_f32_e32 v136, v236, v215
	v_fmac_f32_e32 v137, v236, v248
	v_fmac_f32_e32 v130, v205, v39
	v_fmac_f32_e32 v131, v205, v55
	v_fmac_f32_e32 v132, v205, v216
	v_fmac_f32_e32 v133, v205, v249
	v_fmac_f32_e32 v134, v237, v39
	v_fmac_f32_e32 v135, v237, v55
	v_fmac_f32_e32 v136, v237, v216
	v_fmac_f32_e32 v137, v237, v249
	v_fmac_f32_e32 v130, v206, v40
	v_fmac_f32_e32 v131, v206, v56
	v_fmac_f32_e32 v132, v206, v217
	v_fmac_f32_e32 v133, v206, v250
	v_fmac_f32_e32 v134, v238, v40
	v_fmac_f32_e32 v135, v238, v56
	v_fmac_f32_e32 v136, v238, v217
	v_fmac_f32_e32 v137, v238, v250
	v_fmac_f32_e32 v130, v207, v41
	v_fmac_f32_e32 v131, v207, v57
	v_fmac_f32_e32 v132, v207, v218
	v_fmac_f32_e32 v133, v207, v251
	v_fmac_f32_e32 v134, v239, v41
	v_fmac_f32_e32 v135, v239, v57
	v_fmac_f32_e32 v136, v239, v218
	v_fmac_f32_e32 v137, v239, v251
	v_fmac_f32_e32 v130, v208, v42
	v_fmac_f32_e32 v131, v208, v58
	v_fmac_f32_e32 v132, v208, v219
	v_fmac_f32_e32 v133, v208, v252
	v_fmac_f32_e32 v134, v240, v42
	v_fmac_f32_e32 v135, v240, v58
	v_fmac_f32_e32 v136, v240, v219
	v_fmac_f32_e32 v137, v240, v252
	v_fmac_f32_e32 v130, v209, v43
	v_fmac_f32_e32 v131, v209, v59
	v_fmac_f32_e32 v132, v209, v220
	v_fmac_f32_e32 v133, v209, v253
	v_fmac_f32_e32 v134, v241, v43
	v_fmac_f32_e32 v135, v241, v59
	v_fmac_f32_e32 v136, v241, v220
	v_fmac_f32_e32 v137, v241, v253
	global_load_dwordx4 v[194:197], v4, s[10:11]
	global_load_dwordx4 v[198:201], v4, s[10:11] offset:16
	global_load_dwordx4 v[202:205], v4, s[10:11] offset:32
	global_load_dwordx4 v[206:209], v4, s[10:11] offset:48
	s_add_u32 s10, s10, 0x9000
	s_addc_u32 s11, s11, 0
	global_load_dwordx4 v[226:229], v4, s[10:11]
	global_load_dwordx4 v[230:233], v4, s[10:11] offset:16
	global_load_dwordx4 v[234:237], v4, s[10:11] offset:32
	global_load_dwordx4 v[238:241], v4, s[10:11] offset:48
	s_add_u32 s10, s10, 0x9000
	s_addc_u32 s11, s11, 0
	s_waitcnt vmcnt(8)
	v_mul_f32_e32 v138, v162, v28
	v_mul_f32_e32 v139, v162, v44
	v_mul_f32_e32 v140, v162, v60
	v_mul_f32_e32 v141, v162, v221
	v_mul_f32_e32 v142, v178, v28
	v_mul_f32_e32 v143, v178, v44
	v_mul_f32_e32 v144, v178, v60
	v_mul_f32_e32 v145, v178, v221
	v_fmac_f32_e32 v138, v163, v29
	v_fmac_f32_e32 v139, v163, v45
	v_fmac_f32_e32 v140, v163, v61
	v_fmac_f32_e32 v141, v163, v222
	v_fmac_f32_e32 v142, v179, v29
	v_fmac_f32_e32 v143, v179, v45
	v_fmac_f32_e32 v144, v179, v61
	v_fmac_f32_e32 v145, v179, v222
	v_fmac_f32_e32 v138, v164, v30
	v_fmac_f32_e32 v139, v164, v46
	v_fmac_f32_e32 v140, v164, v62
	v_fmac_f32_e32 v141, v164, v223
	v_fmac_f32_e32 v142, v180, v30
	v_fmac_f32_e32 v143, v180, v46
	v_fmac_f32_e32 v144, v180, v62
	v_fmac_f32_e32 v145, v180, v223
	v_fmac_f32_e32 v138, v165, v31
	v_fmac_f32_e32 v139, v165, v47
	v_fmac_f32_e32 v140, v165, v63
	v_fmac_f32_e32 v141, v165, v224
	v_fmac_f32_e32 v142, v181, v31
	v_fmac_f32_e32 v143, v181, v47
	v_fmac_f32_e32 v144, v181, v63
	v_fmac_f32_e32 v145, v181, v224
	v_fmac_f32_e32 v138, v166, v32
	v_fmac_f32_e32 v139, v166, v48
	v_fmac_f32_e32 v140, v166, v64
	v_fmac_f32_e32 v141, v166, v242
	v_fmac_f32_e32 v142, v182, v32
	v_fmac_f32_e32 v143, v182, v48
	v_fmac_f32_e32 v144, v182, v64
	v_fmac_f32_e32 v145, v182, v242
	v_fmac_f32_e32 v138, v167, v33
	v_fmac_f32_e32 v139, v167, v49
	v_fmac_f32_e32 v140, v167, v65
	v_fmac_f32_e32 v141, v167, v243
	v_fmac_f32_e32 v142, v183, v33
	v_fmac_f32_e32 v143, v183, v49
	v_fmac_f32_e32 v144, v183, v65
	v_fmac_f32_e32 v145, v183, v243
	v_fmac_f32_e32 v138, v168, v34
	v_fmac_f32_e32 v139, v168, v50
	v_fmac_f32_e32 v140, v168, v211
	v_fmac_f32_e32 v141, v168, v244
	v_fmac_f32_e32 v142, v184, v34
	v_fmac_f32_e32 v143, v184, v50
	v_fmac_f32_e32 v144, v184, v211
	v_fmac_f32_e32 v145, v184, v244
	v_fmac_f32_e32 v138, v169, v35
	v_fmac_f32_e32 v139, v169, v51
	v_fmac_f32_e32 v140, v169, v212
	v_fmac_f32_e32 v141, v169, v245
	v_fmac_f32_e32 v142, v185, v35
	v_fmac_f32_e32 v143, v185, v51
	v_fmac_f32_e32 v144, v185, v212
	v_fmac_f32_e32 v145, v185, v245
	v_fmac_f32_e32 v138, v170, v36
	v_fmac_f32_e32 v139, v170, v52
	v_fmac_f32_e32 v140, v170, v213
	v_fmac_f32_e32 v141, v170, v246
	v_fmac_f32_e32 v142, v186, v36
	v_fmac_f32_e32 v143, v186, v52
	v_fmac_f32_e32 v144, v186, v213
	v_fmac_f32_e32 v145, v186, v246
	v_fmac_f32_e32 v138, v171, v37
	v_fmac_f32_e32 v139, v171, v53
	v_fmac_f32_e32 v140, v171, v214
	v_fmac_f32_e32 v141, v171, v247
	v_fmac_f32_e32 v142, v187, v37
	v_fmac_f32_e32 v143, v187, v53
	v_fmac_f32_e32 v144, v187, v214
	v_fmac_f32_e32 v145, v187, v247
	v_fmac_f32_e32 v138, v172, v38
	v_fmac_f32_e32 v139, v172, v54
	v_fmac_f32_e32 v140, v172, v215
	v_fmac_f32_e32 v141, v172, v248
	v_fmac_f32_e32 v142, v188, v38
	v_fmac_f32_e32 v143, v188, v54
	v_fmac_f32_e32 v144, v188, v215
	v_fmac_f32_e32 v145, v188, v248
	v_fmac_f32_e32 v138, v173, v39
	v_fmac_f32_e32 v139, v173, v55
	v_fmac_f32_e32 v140, v173, v216
	v_fmac_f32_e32 v141, v173, v249
	v_fmac_f32_e32 v142, v189, v39
	v_fmac_f32_e32 v143, v189, v55
	v_fmac_f32_e32 v144, v189, v216
	v_fmac_f32_e32 v145, v189, v249
	v_fmac_f32_e32 v138, v174, v40
	v_fmac_f32_e32 v139, v174, v56
	v_fmac_f32_e32 v140, v174, v217
	v_fmac_f32_e32 v141, v174, v250
	v_fmac_f32_e32 v142, v190, v40
	v_fmac_f32_e32 v143, v190, v56
	v_fmac_f32_e32 v144, v190, v217
	v_fmac_f32_e32 v145, v190, v250
	v_fmac_f32_e32 v138, v175, v41
	v_fmac_f32_e32 v139, v175, v57
	v_fmac_f32_e32 v140, v175, v218
	v_fmac_f32_e32 v141, v175, v251
	v_fmac_f32_e32 v142, v191, v41
	v_fmac_f32_e32 v143, v191, v57
	v_fmac_f32_e32 v144, v191, v218
	v_fmac_f32_e32 v145, v191, v251
	v_fmac_f32_e32 v138, v176, v42
	v_fmac_f32_e32 v139, v176, v58
	v_fmac_f32_e32 v140, v176, v219
	v_fmac_f32_e32 v141, v176, v252
	v_fmac_f32_e32 v142, v192, v42
	v_fmac_f32_e32 v143, v192, v58
	v_fmac_f32_e32 v144, v192, v219
	v_fmac_f32_e32 v145, v192, v252
	v_fmac_f32_e32 v138, v177, v43
	v_fmac_f32_e32 v139, v177, v59
	v_fmac_f32_e32 v140, v177, v220
	v_fmac_f32_e32 v141, v177, v253
	v_fmac_f32_e32 v142, v193, v43
	v_fmac_f32_e32 v143, v193, v59
	v_fmac_f32_e32 v144, v193, v220
	v_fmac_f32_e32 v145, v193, v253
	global_load_dwordx4 v[162:165], v4, s[10:11]
	global_load_dwordx4 v[166:169], v4, s[10:11] offset:16
	global_load_dwordx4 v[170:173], v4, s[10:11] offset:32
	global_load_dwordx4 v[174:177], v4, s[10:11] offset:48
	s_add_u32 s10, s10, 0x9000
	s_addc_u32 s11, s11, 0
	global_load_dwordx4 v[178:181], v4, s[10:11]
	global_load_dwordx4 v[182:185], v4, s[10:11] offset:16
	global_load_dwordx4 v[186:189], v4, s[10:11] offset:32
	global_load_dwordx4 v[190:193], v4, s[10:11] offset:48
	s_add_u32 s10, s10, 0x9000
	s_addc_u32 s11, s11, 0
	s_waitcnt vmcnt(8)
	v_mul_f32_e32 v146, v194, v28
	v_mul_f32_e32 v147, v194, v44
	v_mul_f32_e32 v148, v194, v60
	v_mul_f32_e32 v149, v194, v221
	v_mul_f32_e32 v150, v226, v28
	v_mul_f32_e32 v151, v226, v44
	v_mul_f32_e32 v152, v226, v60
	v_mul_f32_e32 v153, v226, v221
	v_fmac_f32_e32 v146, v195, v29
	v_fmac_f32_e32 v147, v195, v45
	v_fmac_f32_e32 v148, v195, v61
	v_fmac_f32_e32 v149, v195, v222
	v_fmac_f32_e32 v150, v227, v29
	v_fmac_f32_e32 v151, v227, v45
	v_fmac_f32_e32 v152, v227, v61
	v_fmac_f32_e32 v153, v227, v222
	v_fmac_f32_e32 v146, v196, v30
	v_fmac_f32_e32 v147, v196, v46
	v_fmac_f32_e32 v148, v196, v62
	v_fmac_f32_e32 v149, v196, v223
	v_fmac_f32_e32 v150, v228, v30
	v_fmac_f32_e32 v151, v228, v46
	v_fmac_f32_e32 v152, v228, v62
	v_fmac_f32_e32 v153, v228, v223
	v_fmac_f32_e32 v146, v197, v31
	v_fmac_f32_e32 v147, v197, v47
	v_fmac_f32_e32 v148, v197, v63
	v_fmac_f32_e32 v149, v197, v224
	v_fmac_f32_e32 v150, v229, v31
	v_fmac_f32_e32 v151, v229, v47
	v_fmac_f32_e32 v152, v229, v63
	v_fmac_f32_e32 v153, v229, v224
	v_fmac_f32_e32 v146, v198, v32
	v_fmac_f32_e32 v147, v198, v48
	v_fmac_f32_e32 v148, v198, v64
	v_fmac_f32_e32 v149, v198, v242
	v_fmac_f32_e32 v150, v230, v32
	v_fmac_f32_e32 v151, v230, v48
	v_fmac_f32_e32 v152, v230, v64
	v_fmac_f32_e32 v153, v230, v242
	v_fmac_f32_e32 v146, v199, v33
	v_fmac_f32_e32 v147, v199, v49
	v_fmac_f32_e32 v148, v199, v65
	v_fmac_f32_e32 v149, v199, v243
	v_fmac_f32_e32 v150, v231, v33
	v_fmac_f32_e32 v151, v231, v49
	v_fmac_f32_e32 v152, v231, v65
	v_fmac_f32_e32 v153, v231, v243
	v_fmac_f32_e32 v146, v200, v34
	v_fmac_f32_e32 v147, v200, v50
	v_fmac_f32_e32 v148, v200, v211
	v_fmac_f32_e32 v149, v200, v244
	v_fmac_f32_e32 v150, v232, v34
	v_fmac_f32_e32 v151, v232, v50
	v_fmac_f32_e32 v152, v232, v211
	v_fmac_f32_e32 v153, v232, v244
	v_fmac_f32_e32 v146, v201, v35
	v_fmac_f32_e32 v147, v201, v51
	v_fmac_f32_e32 v148, v201, v212
	v_fmac_f32_e32 v149, v201, v245
	v_fmac_f32_e32 v150, v233, v35
	v_fmac_f32_e32 v151, v233, v51
	v_fmac_f32_e32 v152, v233, v212
	v_fmac_f32_e32 v153, v233, v245
	v_fmac_f32_e32 v146, v202, v36
	v_fmac_f32_e32 v147, v202, v52
	v_fmac_f32_e32 v148, v202, v213
	v_fmac_f32_e32 v149, v202, v246
	v_fmac_f32_e32 v150, v234, v36
	v_fmac_f32_e32 v151, v234, v52
	v_fmac_f32_e32 v152, v234, v213
	v_fmac_f32_e32 v153, v234, v246
	v_fmac_f32_e32 v146, v203, v37
	v_fmac_f32_e32 v147, v203, v53
	v_fmac_f32_e32 v148, v203, v214
	v_fmac_f32_e32 v149, v203, v247
	v_fmac_f32_e32 v150, v235, v37
	v_fmac_f32_e32 v151, v235, v53
	v_fmac_f32_e32 v152, v235, v214
	v_fmac_f32_e32 v153, v235, v247
	v_fmac_f32_e32 v146, v204, v38
	v_fmac_f32_e32 v147, v204, v54
	v_fmac_f32_e32 v148, v204, v215
	v_fmac_f32_e32 v149, v204, v248
	v_fmac_f32_e32 v150, v236, v38
	v_fmac_f32_e32 v151, v236, v54
	v_fmac_f32_e32 v152, v236, v215
	v_fmac_f32_e32 v153, v236, v248
	v_fmac_f32_e32 v146, v205, v39
	v_fmac_f32_e32 v147, v205, v55
	v_fmac_f32_e32 v148, v205, v216
	v_fmac_f32_e32 v149, v205, v249
	v_fmac_f32_e32 v150, v237, v39
	v_fmac_f32_e32 v151, v237, v55
	v_fmac_f32_e32 v152, v237, v216
	v_fmac_f32_e32 v153, v237, v249
	v_fmac_f32_e32 v146, v206, v40
	v_fmac_f32_e32 v147, v206, v56
	v_fmac_f32_e32 v148, v206, v217
	v_fmac_f32_e32 v149, v206, v250
	v_fmac_f32_e32 v150, v238, v40
	v_fmac_f32_e32 v151, v238, v56
	v_fmac_f32_e32 v152, v238, v217
	v_fmac_f32_e32 v153, v238, v250
	v_fmac_f32_e32 v146, v207, v41
	v_fmac_f32_e32 v147, v207, v57
	v_fmac_f32_e32 v148, v207, v218
	v_fmac_f32_e32 v149, v207, v251
	v_fmac_f32_e32 v150, v239, v41
	v_fmac_f32_e32 v151, v239, v57
	v_fmac_f32_e32 v152, v239, v218
	v_fmac_f32_e32 v153, v239, v251
	v_fmac_f32_e32 v146, v208, v42
	v_fmac_f32_e32 v147, v208, v58
	v_fmac_f32_e32 v148, v208, v219
	v_fmac_f32_e32 v149, v208, v252
	v_fmac_f32_e32 v150, v240, v42
	v_fmac_f32_e32 v151, v240, v58
	v_fmac_f32_e32 v152, v240, v219
	v_fmac_f32_e32 v153, v240, v252
	v_fmac_f32_e32 v146, v209, v43
	v_fmac_f32_e32 v147, v209, v59
	v_fmac_f32_e32 v148, v209, v220
	v_fmac_f32_e32 v149, v209, v253
	v_fmac_f32_e32 v150, v241, v43
	v_fmac_f32_e32 v151, v241, v59
	v_fmac_f32_e32 v152, v241, v220
	v_fmac_f32_e32 v153, v241, v253
	s_waitcnt vmcnt(0)
	v_mul_f32_e32 v154, v162, v28
	v_mul_f32_e32 v155, v162, v44
	v_mul_f32_e32 v156, v162, v60
	v_mul_f32_e32 v157, v162, v221
	v_mul_f32_e32 v158, v178, v28
	v_mul_f32_e32 v159, v178, v44
	v_mul_f32_e32 v160, v178, v60
	v_mul_f32_e32 v161, v178, v221
	v_fmac_f32_e32 v154, v163, v29
	v_fmac_f32_e32 v155, v163, v45
	v_fmac_f32_e32 v156, v163, v61
	v_fmac_f32_e32 v157, v163, v222
	v_fmac_f32_e32 v158, v179, v29
	v_fmac_f32_e32 v159, v179, v45
	v_fmac_f32_e32 v160, v179, v61
	v_fmac_f32_e32 v161, v179, v222
	v_fmac_f32_e32 v154, v164, v30
	v_fmac_f32_e32 v155, v164, v46
	v_fmac_f32_e32 v156, v164, v62
	v_fmac_f32_e32 v157, v164, v223
	v_fmac_f32_e32 v158, v180, v30
	v_fmac_f32_e32 v159, v180, v46
	v_fmac_f32_e32 v160, v180, v62
	v_fmac_f32_e32 v161, v180, v223
	v_fmac_f32_e32 v154, v165, v31
	v_fmac_f32_e32 v155, v165, v47
	v_fmac_f32_e32 v156, v165, v63
	v_fmac_f32_e32 v157, v165, v224
	v_fmac_f32_e32 v158, v181, v31
	v_fmac_f32_e32 v159, v181, v47
	v_fmac_f32_e32 v160, v181, v63
	v_fmac_f32_e32 v161, v181, v224
	v_fmac_f32_e32 v154, v166, v32
	v_fmac_f32_e32 v155, v166, v48
	v_fmac_f32_e32 v156, v166, v64
	v_fmac_f32_e32 v157, v166, v242
	v_fmac_f32_e32 v158, v182, v32
	v_fmac_f32_e32 v159, v182, v48
	v_fmac_f32_e32 v160, v182, v64
	v_fmac_f32_e32 v161, v182, v242
	v_fmac_f32_e32 v154, v167, v33
	v_fmac_f32_e32 v155, v167, v49
	v_fmac_f32_e32 v156, v167, v65
	v_fmac_f32_e32 v157, v167, v243
	v_fmac_f32_e32 v158, v183, v33
	v_fmac_f32_e32 v159, v183, v49
	v_fmac_f32_e32 v160, v183, v65
	v_fmac_f32_e32 v161, v183, v243
	v_fmac_f32_e32 v154, v168, v34
	v_fmac_f32_e32 v155, v168, v50
	v_fmac_f32_e32 v156, v168, v211
	v_fmac_f32_e32 v157, v168, v244
	v_fmac_f32_e32 v158, v184, v34
	v_fmac_f32_e32 v159, v184, v50
	v_fmac_f32_e32 v160, v184, v211
	v_fmac_f32_e32 v161, v184, v244
	v_fmac_f32_e32 v154, v169, v35
	v_fmac_f32_e32 v155, v169, v51
	v_fmac_f32_e32 v156, v169, v212
	v_fmac_f32_e32 v157, v169, v245
	v_fmac_f32_e32 v158, v185, v35
	v_fmac_f32_e32 v159, v185, v51
	v_fmac_f32_e32 v160, v185, v212
	v_fmac_f32_e32 v161, v185, v245
	v_fmac_f32_e32 v154, v170, v36
	v_fmac_f32_e32 v155, v170, v52
	v_fmac_f32_e32 v156, v170, v213
	v_fmac_f32_e32 v157, v170, v246
	v_fmac_f32_e32 v158, v186, v36
	v_fmac_f32_e32 v159, v186, v52
	v_fmac_f32_e32 v160, v186, v213
	v_fmac_f32_e32 v161, v186, v246
	v_fmac_f32_e32 v154, v171, v37
	v_fmac_f32_e32 v155, v171, v53
	v_fmac_f32_e32 v156, v171, v214
	v_fmac_f32_e32 v157, v171, v247
	v_fmac_f32_e32 v158, v187, v37
	v_fmac_f32_e32 v159, v187, v53
	v_fmac_f32_e32 v160, v187, v214
	v_fmac_f32_e32 v161, v187, v247
	v_fmac_f32_e32 v154, v172, v38
	v_fmac_f32_e32 v155, v172, v54
	v_fmac_f32_e32 v156, v172, v215
	v_fmac_f32_e32 v157, v172, v248
	v_fmac_f32_e32 v158, v188, v38
	v_fmac_f32_e32 v159, v188, v54
	v_fmac_f32_e32 v160, v188, v215
	v_fmac_f32_e32 v161, v188, v248
	v_fmac_f32_e32 v154, v173, v39
	v_fmac_f32_e32 v155, v173, v55
	v_fmac_f32_e32 v156, v173, v216
	v_fmac_f32_e32 v157, v173, v249
	v_fmac_f32_e32 v158, v189, v39
	v_fmac_f32_e32 v159, v189, v55
	v_fmac_f32_e32 v160, v189, v216
	v_fmac_f32_e32 v161, v189, v249
	v_fmac_f32_e32 v154, v174, v40
	v_fmac_f32_e32 v155, v174, v56
	v_fmac_f32_e32 v156, v174, v217
	v_fmac_f32_e32 v157, v174, v250
	v_fmac_f32_e32 v158, v190, v40
	v_fmac_f32_e32 v159, v190, v56
	v_fmac_f32_e32 v160, v190, v217
	v_fmac_f32_e32 v161, v190, v250
	v_fmac_f32_e32 v154, v175, v41
	v_fmac_f32_e32 v155, v175, v57
	v_fmac_f32_e32 v156, v175, v218
	v_fmac_f32_e32 v157, v175, v251
	v_fmac_f32_e32 v158, v191, v41
	v_fmac_f32_e32 v159, v191, v57
	v_fmac_f32_e32 v160, v191, v218
	v_fmac_f32_e32 v161, v191, v251
	v_fmac_f32_e32 v154, v176, v42
	v_fmac_f32_e32 v155, v176, v58
	v_fmac_f32_e32 v156, v176, v219
	v_fmac_f32_e32 v157, v176, v252
	v_fmac_f32_e32 v158, v192, v42
	v_fmac_f32_e32 v159, v192, v58
	v_fmac_f32_e32 v160, v192, v219
	v_fmac_f32_e32 v161, v192, v252
	v_fmac_f32_e32 v154, v177, v43
	v_fmac_f32_e32 v155, v177, v59
	v_fmac_f32_e32 v156, v177, v220
	v_fmac_f32_e32 v157, v177, v253
	v_fmac_f32_e32 v158, v193, v43
	v_fmac_f32_e32 v159, v193, v59
	v_fmac_f32_e32 v160, v193, v220
	v_fmac_f32_e32 v161, v193, v253
	v_add_f32_dpp v98, v98, v98 quad_perm:[1,0,3,2] row_mask:0xf bank_mask:0xf
	v_add_f32_dpp v99, v99, v99 quad_perm:[1,0,3,2] row_mask:0xf bank_mask:0xf
	v_add_f32_dpp v100, v100, v100 quad_perm:[1,0,3,2] row_mask:0xf bank_mask:0xf
	v_add_f32_dpp v101, v101, v101 quad_perm:[1,0,3,2] row_mask:0xf bank_mask:0xf
	v_add_f32_dpp v102, v102, v102 quad_perm:[1,0,3,2] row_mask:0xf bank_mask:0xf
	v_add_f32_dpp v103, v103, v103 quad_perm:[1,0,3,2] row_mask:0xf bank_mask:0xf
	v_add_f32_dpp v104, v104, v104 quad_perm:[1,0,3,2] row_mask:0xf bank_mask:0xf
	v_add_f32_dpp v105, v105, v105 quad_perm:[1,0,3,2] row_mask:0xf bank_mask:0xf
	v_add_f32_dpp v106, v106, v106 quad_perm:[1,0,3,2] row_mask:0xf bank_mask:0xf
	v_add_f32_dpp v107, v107, v107 quad_perm:[1,0,3,2] row_mask:0xf bank_mask:0xf
	v_add_f32_dpp v108, v108, v108 quad_perm:[1,0,3,2] row_mask:0xf bank_mask:0xf
	v_add_f32_dpp v109, v109, v109 quad_perm:[1,0,3,2] row_mask:0xf bank_mask:0xf
	v_add_f32_dpp v110, v110, v110 quad_perm:[1,0,3,2] row_mask:0xf bank_mask:0xf
	v_add_f32_dpp v111, v111, v111 quad_perm:[1,0,3,2] row_mask:0xf bank_mask:0xf
	v_add_f32_dpp v112, v112, v112 quad_perm:[1,0,3,2] row_mask:0xf bank_mask:0xf
	v_add_f32_dpp v113, v113, v113 quad_perm:[1,0,3,2] row_mask:0xf bank_mask:0xf
	v_add_f32_dpp v114, v114, v114 quad_perm:[1,0,3,2] row_mask:0xf bank_mask:0xf
	v_add_f32_dpp v115, v115, v115 quad_perm:[1,0,3,2] row_mask:0xf bank_mask:0xf
	v_add_f32_dpp v116, v116, v116 quad_perm:[1,0,3,2] row_mask:0xf bank_mask:0xf
	v_add_f32_dpp v117, v117, v117 quad_perm:[1,0,3,2] row_mask:0xf bank_mask:0xf
	v_add_f32_dpp v118, v118, v118 quad_perm:[1,0,3,2] row_mask:0xf bank_mask:0xf
	v_add_f32_dpp v119, v119, v119 quad_perm:[1,0,3,2] row_mask:0xf bank_mask:0xf
	v_add_f32_dpp v120, v120, v120 quad_perm:[1,0,3,2] row_mask:0xf bank_mask:0xf
	v_add_f32_dpp v121, v121, v121 quad_perm:[1,0,3,2] row_mask:0xf bank_mask:0xf
	v_add_f32_dpp v122, v122, v122 quad_perm:[1,0,3,2] row_mask:0xf bank_mask:0xf
	v_add_f32_dpp v123, v123, v123 quad_perm:[1,0,3,2] row_mask:0xf bank_mask:0xf
	v_add_f32_dpp v124, v124, v124 quad_perm:[1,0,3,2] row_mask:0xf bank_mask:0xf
	v_add_f32_dpp v125, v125, v125 quad_perm:[1,0,3,2] row_mask:0xf bank_mask:0xf
	v_add_f32_dpp v126, v126, v126 quad_perm:[1,0,3,2] row_mask:0xf bank_mask:0xf
	v_add_f32_dpp v127, v127, v127 quad_perm:[1,0,3,2] row_mask:0xf bank_mask:0xf
	v_add_f32_dpp v128, v128, v128 quad_perm:[1,0,3,2] row_mask:0xf bank_mask:0xf
	v_add_f32_dpp v129, v129, v129 quad_perm:[1,0,3,2] row_mask:0xf bank_mask:0xf
	v_add_f32_dpp v130, v130, v130 quad_perm:[1,0,3,2] row_mask:0xf bank_mask:0xf
	v_add_f32_dpp v131, v131, v131 quad_perm:[1,0,3,2] row_mask:0xf bank_mask:0xf
	v_add_f32_dpp v132, v132, v132 quad_perm:[1,0,3,2] row_mask:0xf bank_mask:0xf
	v_add_f32_dpp v133, v133, v133 quad_perm:[1,0,3,2] row_mask:0xf bank_mask:0xf
	v_add_f32_dpp v134, v134, v134 quad_perm:[1,0,3,2] row_mask:0xf bank_mask:0xf
	v_add_f32_dpp v135, v135, v135 quad_perm:[1,0,3,2] row_mask:0xf bank_mask:0xf
	v_add_f32_dpp v136, v136, v136 quad_perm:[1,0,3,2] row_mask:0xf bank_mask:0xf
	v_add_f32_dpp v137, v137, v137 quad_perm:[1,0,3,2] row_mask:0xf bank_mask:0xf
	v_add_f32_dpp v138, v138, v138 quad_perm:[1,0,3,2] row_mask:0xf bank_mask:0xf
	v_add_f32_dpp v139, v139, v139 quad_perm:[1,0,3,2] row_mask:0xf bank_mask:0xf
	v_add_f32_dpp v140, v140, v140 quad_perm:[1,0,3,2] row_mask:0xf bank_mask:0xf
	v_add_f32_dpp v141, v141, v141 quad_perm:[1,0,3,2] row_mask:0xf bank_mask:0xf
	v_add_f32_dpp v142, v142, v142 quad_perm:[1,0,3,2] row_mask:0xf bank_mask:0xf
	v_add_f32_dpp v143, v143, v143 quad_perm:[1,0,3,2] row_mask:0xf bank_mask:0xf
	v_add_f32_dpp v144, v144, v144 quad_perm:[1,0,3,2] row_mask:0xf bank_mask:0xf
	v_add_f32_dpp v145, v145, v145 quad_perm:[1,0,3,2] row_mask:0xf bank_mask:0xf
	v_add_f32_dpp v146, v146, v146 quad_perm:[1,0,3,2] row_mask:0xf bank_mask:0xf
	v_add_f32_dpp v147, v147, v147 quad_perm:[1,0,3,2] row_mask:0xf bank_mask:0xf
	v_add_f32_dpp v148, v148, v148 quad_perm:[1,0,3,2] row_mask:0xf bank_mask:0xf
	v_add_f32_dpp v149, v149, v149 quad_perm:[1,0,3,2] row_mask:0xf bank_mask:0xf
	v_add_f32_dpp v150, v150, v150 quad_perm:[1,0,3,2] row_mask:0xf bank_mask:0xf
	v_add_f32_dpp v151, v151, v151 quad_perm:[1,0,3,2] row_mask:0xf bank_mask:0xf
	v_add_f32_dpp v152, v152, v152 quad_perm:[1,0,3,2] row_mask:0xf bank_mask:0xf
	v_add_f32_dpp v153, v153, v153 quad_perm:[1,0,3,2] row_mask:0xf bank_mask:0xf
	v_add_f32_dpp v154, v154, v154 quad_perm:[1,0,3,2] row_mask:0xf bank_mask:0xf
	v_add_f32_dpp v155, v155, v155 quad_perm:[1,0,3,2] row_mask:0xf bank_mask:0xf
	v_add_f32_dpp v156, v156, v156 quad_perm:[1,0,3,2] row_mask:0xf bank_mask:0xf
	v_add_f32_dpp v157, v157, v157 quad_perm:[1,0,3,2] row_mask:0xf bank_mask:0xf
	v_add_f32_dpp v158, v158, v158 quad_perm:[1,0,3,2] row_mask:0xf bank_mask:0xf
	v_add_f32_dpp v159, v159, v159 quad_perm:[1,0,3,2] row_mask:0xf bank_mask:0xf
	v_add_f32_dpp v160, v160, v160 quad_perm:[1,0,3,2] row_mask:0xf bank_mask:0xf
	v_add_f32_dpp v161, v161, v161 quad_perm:[1,0,3,2] row_mask:0xf bank_mask:0xf
	v_add_f32_dpp v98, v98, v98 quad_perm:[2,3,0,1] row_mask:0xf bank_mask:0xf
	v_add_f32_dpp v99, v99, v99 quad_perm:[2,3,0,1] row_mask:0xf bank_mask:0xf
	v_add_f32_dpp v100, v100, v100 quad_perm:[2,3,0,1] row_mask:0xf bank_mask:0xf
	v_add_f32_dpp v101, v101, v101 quad_perm:[2,3,0,1] row_mask:0xf bank_mask:0xf
	v_add_f32_dpp v102, v102, v102 quad_perm:[2,3,0,1] row_mask:0xf bank_mask:0xf
	v_add_f32_dpp v103, v103, v103 quad_perm:[2,3,0,1] row_mask:0xf bank_mask:0xf
	v_add_f32_dpp v104, v104, v104 quad_perm:[2,3,0,1] row_mask:0xf bank_mask:0xf
	v_add_f32_dpp v105, v105, v105 quad_perm:[2,3,0,1] row_mask:0xf bank_mask:0xf
	v_add_f32_dpp v106, v106, v106 quad_perm:[2,3,0,1] row_mask:0xf bank_mask:0xf
	v_add_f32_dpp v107, v107, v107 quad_perm:[2,3,0,1] row_mask:0xf bank_mask:0xf
	v_add_f32_dpp v108, v108, v108 quad_perm:[2,3,0,1] row_mask:0xf bank_mask:0xf
	v_add_f32_dpp v109, v109, v109 quad_perm:[2,3,0,1] row_mask:0xf bank_mask:0xf
	v_add_f32_dpp v110, v110, v110 quad_perm:[2,3,0,1] row_mask:0xf bank_mask:0xf
	v_add_f32_dpp v111, v111, v111 quad_perm:[2,3,0,1] row_mask:0xf bank_mask:0xf
	v_add_f32_dpp v112, v112, v112 quad_perm:[2,3,0,1] row_mask:0xf bank_mask:0xf
	v_add_f32_dpp v113, v113, v113 quad_perm:[2,3,0,1] row_mask:0xf bank_mask:0xf
	v_add_f32_dpp v114, v114, v114 quad_perm:[2,3,0,1] row_mask:0xf bank_mask:0xf
	v_add_f32_dpp v115, v115, v115 quad_perm:[2,3,0,1] row_mask:0xf bank_mask:0xf
	v_add_f32_dpp v116, v116, v116 quad_perm:[2,3,0,1] row_mask:0xf bank_mask:0xf
	v_add_f32_dpp v117, v117, v117 quad_perm:[2,3,0,1] row_mask:0xf bank_mask:0xf
	v_add_f32_dpp v118, v118, v118 quad_perm:[2,3,0,1] row_mask:0xf bank_mask:0xf
	v_add_f32_dpp v119, v119, v119 quad_perm:[2,3,0,1] row_mask:0xf bank_mask:0xf
	v_add_f32_dpp v120, v120, v120 quad_perm:[2,3,0,1] row_mask:0xf bank_mask:0xf
	v_add_f32_dpp v121, v121, v121 quad_perm:[2,3,0,1] row_mask:0xf bank_mask:0xf
	v_add_f32_dpp v122, v122, v122 quad_perm:[2,3,0,1] row_mask:0xf bank_mask:0xf
	v_add_f32_dpp v123, v123, v123 quad_perm:[2,3,0,1] row_mask:0xf bank_mask:0xf
	v_add_f32_dpp v124, v124, v124 quad_perm:[2,3,0,1] row_mask:0xf bank_mask:0xf
	v_add_f32_dpp v125, v125, v125 quad_perm:[2,3,0,1] row_mask:0xf bank_mask:0xf
	v_add_f32_dpp v126, v126, v126 quad_perm:[2,3,0,1] row_mask:0xf bank_mask:0xf
	v_add_f32_dpp v127, v127, v127 quad_perm:[2,3,0,1] row_mask:0xf bank_mask:0xf
	v_add_f32_dpp v128, v128, v128 quad_perm:[2,3,0,1] row_mask:0xf bank_mask:0xf
	v_add_f32_dpp v129, v129, v129 quad_perm:[2,3,0,1] row_mask:0xf bank_mask:0xf
	v_add_f32_dpp v130, v130, v130 quad_perm:[2,3,0,1] row_mask:0xf bank_mask:0xf
	v_add_f32_dpp v131, v131, v131 quad_perm:[2,3,0,1] row_mask:0xf bank_mask:0xf
	v_add_f32_dpp v132, v132, v132 quad_perm:[2,3,0,1] row_mask:0xf bank_mask:0xf
	v_add_f32_dpp v133, v133, v133 quad_perm:[2,3,0,1] row_mask:0xf bank_mask:0xf
	v_add_f32_dpp v134, v134, v134 quad_perm:[2,3,0,1] row_mask:0xf bank_mask:0xf
	v_add_f32_dpp v135, v135, v135 quad_perm:[2,3,0,1] row_mask:0xf bank_mask:0xf
	v_add_f32_dpp v136, v136, v136 quad_perm:[2,3,0,1] row_mask:0xf bank_mask:0xf
	v_add_f32_dpp v137, v137, v137 quad_perm:[2,3,0,1] row_mask:0xf bank_mask:0xf
	v_add_f32_dpp v138, v138, v138 quad_perm:[2,3,0,1] row_mask:0xf bank_mask:0xf
	v_add_f32_dpp v139, v139, v139 quad_perm:[2,3,0,1] row_mask:0xf bank_mask:0xf
	v_add_f32_dpp v140, v140, v140 quad_perm:[2,3,0,1] row_mask:0xf bank_mask:0xf
	v_add_f32_dpp v141, v141, v141 quad_perm:[2,3,0,1] row_mask:0xf bank_mask:0xf
	v_add_f32_dpp v142, v142, v142 quad_perm:[2,3,0,1] row_mask:0xf bank_mask:0xf
	v_add_f32_dpp v143, v143, v143 quad_perm:[2,3,0,1] row_mask:0xf bank_mask:0xf
	v_add_f32_dpp v144, v144, v144 quad_perm:[2,3,0,1] row_mask:0xf bank_mask:0xf
	v_add_f32_dpp v145, v145, v145 quad_perm:[2,3,0,1] row_mask:0xf bank_mask:0xf
	v_add_f32_dpp v146, v146, v146 quad_perm:[2,3,0,1] row_mask:0xf bank_mask:0xf
	v_add_f32_dpp v147, v147, v147 quad_perm:[2,3,0,1] row_mask:0xf bank_mask:0xf
	v_add_f32_dpp v148, v148, v148 quad_perm:[2,3,0,1] row_mask:0xf bank_mask:0xf
	v_add_f32_dpp v149, v149, v149 quad_perm:[2,3,0,1] row_mask:0xf bank_mask:0xf
	v_add_f32_dpp v150, v150, v150 quad_perm:[2,3,0,1] row_mask:0xf bank_mask:0xf
	v_add_f32_dpp v151, v151, v151 quad_perm:[2,3,0,1] row_mask:0xf bank_mask:0xf
	v_add_f32_dpp v152, v152, v152 quad_perm:[2,3,0,1] row_mask:0xf bank_mask:0xf
	v_add_f32_dpp v153, v153, v153 quad_perm:[2,3,0,1] row_mask:0xf bank_mask:0xf
	v_add_f32_dpp v154, v154, v154 quad_perm:[2,3,0,1] row_mask:0xf bank_mask:0xf
	v_add_f32_dpp v155, v155, v155 quad_perm:[2,3,0,1] row_mask:0xf bank_mask:0xf
	v_add_f32_dpp v156, v156, v156 quad_perm:[2,3,0,1] row_mask:0xf bank_mask:0xf
	v_add_f32_dpp v157, v157, v157 quad_perm:[2,3,0,1] row_mask:0xf bank_mask:0xf
	v_add_f32_dpp v158, v158, v158 quad_perm:[2,3,0,1] row_mask:0xf bank_mask:0xf
	v_add_f32_dpp v159, v159, v159 quad_perm:[2,3,0,1] row_mask:0xf bank_mask:0xf
	v_add_f32_dpp v160, v160, v160 quad_perm:[2,3,0,1] row_mask:0xf bank_mask:0xf
	v_add_f32_dpp v161, v161, v161 quad_perm:[2,3,0,1] row_mask:0xf bank_mask:0xf
	v_add_f32_dpp v98, v98, v98 row_half_mirror row_mask:0xf bank_mask:0xf
	v_add_f32_dpp v99, v99, v99 row_half_mirror row_mask:0xf bank_mask:0xf
	v_add_f32_dpp v100, v100, v100 row_half_mirror row_mask:0xf bank_mask:0xf
	v_add_f32_dpp v101, v101, v101 row_half_mirror row_mask:0xf bank_mask:0xf
	v_add_f32_dpp v102, v102, v102 row_half_mirror row_mask:0xf bank_mask:0xf
	v_add_f32_dpp v103, v103, v103 row_half_mirror row_mask:0xf bank_mask:0xf
	v_add_f32_dpp v104, v104, v104 row_half_mirror row_mask:0xf bank_mask:0xf
	v_add_f32_dpp v105, v105, v105 row_half_mirror row_mask:0xf bank_mask:0xf
	v_add_f32_dpp v106, v106, v106 row_half_mirror row_mask:0xf bank_mask:0xf
	v_add_f32_dpp v107, v107, v107 row_half_mirror row_mask:0xf bank_mask:0xf
	v_add_f32_dpp v108, v108, v108 row_half_mirror row_mask:0xf bank_mask:0xf
	v_add_f32_dpp v109, v109, v109 row_half_mirror row_mask:0xf bank_mask:0xf
	v_add_f32_dpp v110, v110, v110 row_half_mirror row_mask:0xf bank_mask:0xf
	v_add_f32_dpp v111, v111, v111 row_half_mirror row_mask:0xf bank_mask:0xf
	v_add_f32_dpp v112, v112, v112 row_half_mirror row_mask:0xf bank_mask:0xf
	v_add_f32_dpp v113, v113, v113 row_half_mirror row_mask:0xf bank_mask:0xf
	v_add_f32_dpp v114, v114, v114 row_half_mirror row_mask:0xf bank_mask:0xf
	v_add_f32_dpp v115, v115, v115 row_half_mirror row_mask:0xf bank_mask:0xf
	v_add_f32_dpp v116, v116, v116 row_half_mirror row_mask:0xf bank_mask:0xf
	v_add_f32_dpp v117, v117, v117 row_half_mirror row_mask:0xf bank_mask:0xf
	v_add_f32_dpp v118, v118, v118 row_half_mirror row_mask:0xf bank_mask:0xf
	v_add_f32_dpp v119, v119, v119 row_half_mirror row_mask:0xf bank_mask:0xf
	v_add_f32_dpp v120, v120, v120 row_half_mirror row_mask:0xf bank_mask:0xf
	v_add_f32_dpp v121, v121, v121 row_half_mirror row_mask:0xf bank_mask:0xf
	v_add_f32_dpp v122, v122, v122 row_half_mirror row_mask:0xf bank_mask:0xf
	v_add_f32_dpp v123, v123, v123 row_half_mirror row_mask:0xf bank_mask:0xf
	v_add_f32_dpp v124, v124, v124 row_half_mirror row_mask:0xf bank_mask:0xf
	v_add_f32_dpp v125, v125, v125 row_half_mirror row_mask:0xf bank_mask:0xf
	v_add_f32_dpp v126, v126, v126 row_half_mirror row_mask:0xf bank_mask:0xf
	v_add_f32_dpp v127, v127, v127 row_half_mirror row_mask:0xf bank_mask:0xf
	v_add_f32_dpp v128, v128, v128 row_half_mirror row_mask:0xf bank_mask:0xf
	v_add_f32_dpp v129, v129, v129 row_half_mirror row_mask:0xf bank_mask:0xf
	v_add_f32_dpp v130, v130, v130 row_half_mirror row_mask:0xf bank_mask:0xf
	v_add_f32_dpp v131, v131, v131 row_half_mirror row_mask:0xf bank_mask:0xf
	v_add_f32_dpp v132, v132, v132 row_half_mirror row_mask:0xf bank_mask:0xf
	v_add_f32_dpp v133, v133, v133 row_half_mirror row_mask:0xf bank_mask:0xf
	v_add_f32_dpp v134, v134, v134 row_half_mirror row_mask:0xf bank_mask:0xf
	v_add_f32_dpp v135, v135, v135 row_half_mirror row_mask:0xf bank_mask:0xf
	v_add_f32_dpp v136, v136, v136 row_half_mirror row_mask:0xf bank_mask:0xf
	v_add_f32_dpp v137, v137, v137 row_half_mirror row_mask:0xf bank_mask:0xf
	v_add_f32_dpp v138, v138, v138 row_half_mirror row_mask:0xf bank_mask:0xf
	v_add_f32_dpp v139, v139, v139 row_half_mirror row_mask:0xf bank_mask:0xf
	v_add_f32_dpp v140, v140, v140 row_half_mirror row_mask:0xf bank_mask:0xf
	v_add_f32_dpp v141, v141, v141 row_half_mirror row_mask:0xf bank_mask:0xf
	v_add_f32_dpp v142, v142, v142 row_half_mirror row_mask:0xf bank_mask:0xf
	v_add_f32_dpp v143, v143, v143 row_half_mirror row_mask:0xf bank_mask:0xf
	v_add_f32_dpp v144, v144, v144 row_half_mirror row_mask:0xf bank_mask:0xf
	v_add_f32_dpp v145, v145, v145 row_half_mirror row_mask:0xf bank_mask:0xf
	v_add_f32_dpp v146, v146, v146 row_half_mirror row_mask:0xf bank_mask:0xf
	v_add_f32_dpp v147, v147, v147 row_half_mirror row_mask:0xf bank_mask:0xf
	v_add_f32_dpp v148, v148, v148 row_half_mirror row_mask:0xf bank_mask:0xf
	v_add_f32_dpp v149, v149, v149 row_half_mirror row_mask:0xf bank_mask:0xf
	v_add_f32_dpp v150, v150, v150 row_half_mirror row_mask:0xf bank_mask:0xf
	v_add_f32_dpp v151, v151, v151 row_half_mirror row_mask:0xf bank_mask:0xf
	v_add_f32_dpp v152, v152, v152 row_half_mirror row_mask:0xf bank_mask:0xf
	v_add_f32_dpp v153, v153, v153 row_half_mirror row_mask:0xf bank_mask:0xf
	v_add_f32_dpp v154, v154, v154 row_half_mirror row_mask:0xf bank_mask:0xf
	v_add_f32_dpp v155, v155, v155 row_half_mirror row_mask:0xf bank_mask:0xf
	v_add_f32_dpp v156, v156, v156 row_half_mirror row_mask:0xf bank_mask:0xf
	v_add_f32_dpp v157, v157, v157 row_half_mirror row_mask:0xf bank_mask:0xf
	v_add_f32_dpp v158, v158, v158 row_half_mirror row_mask:0xf bank_mask:0xf
	v_add_f32_dpp v159, v159, v159 row_half_mirror row_mask:0xf bank_mask:0xf
	v_add_f32_dpp v160, v160, v160 row_half_mirror row_mask:0xf bank_mask:0xf
	v_add_f32_dpp v161, v161, v161 row_half_mirror row_mask:0xf bank_mask:0xf
	v_add_f32_dpp v98, v98, v98 row_mirror row_mask:0xf bank_mask:0xf
	v_add_f32_dpp v99, v99, v99 row_mirror row_mask:0xf bank_mask:0xf
	v_add_f32_dpp v100, v100, v100 row_mirror row_mask:0xf bank_mask:0xf
	v_add_f32_dpp v101, v101, v101 row_mirror row_mask:0xf bank_mask:0xf
	v_add_f32_dpp v102, v102, v102 row_mirror row_mask:0xf bank_mask:0xf
	v_add_f32_dpp v103, v103, v103 row_mirror row_mask:0xf bank_mask:0xf
	v_add_f32_dpp v104, v104, v104 row_mirror row_mask:0xf bank_mask:0xf
	v_add_f32_dpp v105, v105, v105 row_mirror row_mask:0xf bank_mask:0xf
	v_add_f32_dpp v106, v106, v106 row_mirror row_mask:0xf bank_mask:0xf
	v_add_f32_dpp v107, v107, v107 row_mirror row_mask:0xf bank_mask:0xf
	v_add_f32_dpp v108, v108, v108 row_mirror row_mask:0xf bank_mask:0xf
	v_add_f32_dpp v109, v109, v109 row_mirror row_mask:0xf bank_mask:0xf
	v_add_f32_dpp v110, v110, v110 row_mirror row_mask:0xf bank_mask:0xf
	v_add_f32_dpp v111, v111, v111 row_mirror row_mask:0xf bank_mask:0xf
	v_add_f32_dpp v112, v112, v112 row_mirror row_mask:0xf bank_mask:0xf
	v_add_f32_dpp v113, v113, v113 row_mirror row_mask:0xf bank_mask:0xf
	v_add_f32_dpp v114, v114, v114 row_mirror row_mask:0xf bank_mask:0xf
	v_add_f32_dpp v115, v115, v115 row_mirror row_mask:0xf bank_mask:0xf
	v_add_f32_dpp v116, v116, v116 row_mirror row_mask:0xf bank_mask:0xf
	v_add_f32_dpp v117, v117, v117 row_mirror row_mask:0xf bank_mask:0xf
	v_add_f32_dpp v118, v118, v118 row_mirror row_mask:0xf bank_mask:0xf
	v_add_f32_dpp v119, v119, v119 row_mirror row_mask:0xf bank_mask:0xf
	v_add_f32_dpp v120, v120, v120 row_mirror row_mask:0xf bank_mask:0xf
	v_add_f32_dpp v121, v121, v121 row_mirror row_mask:0xf bank_mask:0xf
	v_add_f32_dpp v122, v122, v122 row_mirror row_mask:0xf bank_mask:0xf
	v_add_f32_dpp v123, v123, v123 row_mirror row_mask:0xf bank_mask:0xf
	v_add_f32_dpp v124, v124, v124 row_mirror row_mask:0xf bank_mask:0xf
	v_add_f32_dpp v125, v125, v125 row_mirror row_mask:0xf bank_mask:0xf
	v_add_f32_dpp v126, v126, v126 row_mirror row_mask:0xf bank_mask:0xf
	v_add_f32_dpp v127, v127, v127 row_mirror row_mask:0xf bank_mask:0xf
	v_add_f32_dpp v128, v128, v128 row_mirror row_mask:0xf bank_mask:0xf
	v_add_f32_dpp v129, v129, v129 row_mirror row_mask:0xf bank_mask:0xf
	v_add_f32_dpp v130, v130, v130 row_mirror row_mask:0xf bank_mask:0xf
	v_add_f32_dpp v131, v131, v131 row_mirror row_mask:0xf bank_mask:0xf
	v_add_f32_dpp v132, v132, v132 row_mirror row_mask:0xf bank_mask:0xf
	v_add_f32_dpp v133, v133, v133 row_mirror row_mask:0xf bank_mask:0xf
	v_add_f32_dpp v134, v134, v134 row_mirror row_mask:0xf bank_mask:0xf
	v_add_f32_dpp v135, v135, v135 row_mirror row_mask:0xf bank_mask:0xf
	v_add_f32_dpp v136, v136, v136 row_mirror row_mask:0xf bank_mask:0xf
	v_add_f32_dpp v137, v137, v137 row_mirror row_mask:0xf bank_mask:0xf
	v_add_f32_dpp v138, v138, v138 row_mirror row_mask:0xf bank_mask:0xf
	v_add_f32_dpp v139, v139, v139 row_mirror row_mask:0xf bank_mask:0xf
	v_add_f32_dpp v140, v140, v140 row_mirror row_mask:0xf bank_mask:0xf
	v_add_f32_dpp v141, v141, v141 row_mirror row_mask:0xf bank_mask:0xf
	v_add_f32_dpp v142, v142, v142 row_mirror row_mask:0xf bank_mask:0xf
	v_add_f32_dpp v143, v143, v143 row_mirror row_mask:0xf bank_mask:0xf
	v_add_f32_dpp v144, v144, v144 row_mirror row_mask:0xf bank_mask:0xf
	v_add_f32_dpp v145, v145, v145 row_mirror row_mask:0xf bank_mask:0xf
	v_add_f32_dpp v146, v146, v146 row_mirror row_mask:0xf bank_mask:0xf
	v_add_f32_dpp v147, v147, v147 row_mirror row_mask:0xf bank_mask:0xf
	v_add_f32_dpp v148, v148, v148 row_mirror row_mask:0xf bank_mask:0xf
	v_add_f32_dpp v149, v149, v149 row_mirror row_mask:0xf bank_mask:0xf
	v_add_f32_dpp v150, v150, v150 row_mirror row_mask:0xf bank_mask:0xf
	v_add_f32_dpp v151, v151, v151 row_mirror row_mask:0xf bank_mask:0xf
	v_add_f32_dpp v152, v152, v152 row_mirror row_mask:0xf bank_mask:0xf
	v_add_f32_dpp v153, v153, v153 row_mirror row_mask:0xf bank_mask:0xf
	v_add_f32_dpp v154, v154, v154 row_mirror row_mask:0xf bank_mask:0xf
	v_add_f32_dpp v155, v155, v155 row_mirror row_mask:0xf bank_mask:0xf
	v_add_f32_dpp v156, v156, v156 row_mirror row_mask:0xf bank_mask:0xf
	v_add_f32_dpp v157, v157, v157 row_mirror row_mask:0xf bank_mask:0xf
	v_add_f32_dpp v158, v158, v158 row_mirror row_mask:0xf bank_mask:0xf
	v_add_f32_dpp v159, v159, v159 row_mirror row_mask:0xf bank_mask:0xf
	v_add_f32_dpp v160, v160, v160 row_mirror row_mask:0xf bank_mask:0xf
	v_add_f32_dpp v161, v161, v161 row_mirror row_mask:0xf bank_mask:0xf
	v_add_f32_dpp v98, v98, v98 row_bcast:15 row_mask:0xa bank_mask:0xf
	v_add_f32_dpp v99, v99, v99 row_bcast:15 row_mask:0xa bank_mask:0xf
	v_add_f32_dpp v100, v100, v100 row_bcast:15 row_mask:0xa bank_mask:0xf
	v_add_f32_dpp v101, v101, v101 row_bcast:15 row_mask:0xa bank_mask:0xf
	v_add_f32_dpp v102, v102, v102 row_bcast:15 row_mask:0xa bank_mask:0xf
	v_add_f32_dpp v103, v103, v103 row_bcast:15 row_mask:0xa bank_mask:0xf
	v_add_f32_dpp v104, v104, v104 row_bcast:15 row_mask:0xa bank_mask:0xf
	v_add_f32_dpp v105, v105, v105 row_bcast:15 row_mask:0xa bank_mask:0xf
	v_add_f32_dpp v106, v106, v106 row_bcast:15 row_mask:0xa bank_mask:0xf
	v_add_f32_dpp v107, v107, v107 row_bcast:15 row_mask:0xa bank_mask:0xf
	v_add_f32_dpp v108, v108, v108 row_bcast:15 row_mask:0xa bank_mask:0xf
	v_add_f32_dpp v109, v109, v109 row_bcast:15 row_mask:0xa bank_mask:0xf
	v_add_f32_dpp v110, v110, v110 row_bcast:15 row_mask:0xa bank_mask:0xf
	v_add_f32_dpp v111, v111, v111 row_bcast:15 row_mask:0xa bank_mask:0xf
	v_add_f32_dpp v112, v112, v112 row_bcast:15 row_mask:0xa bank_mask:0xf
	v_add_f32_dpp v113, v113, v113 row_bcast:15 row_mask:0xa bank_mask:0xf
	v_add_f32_dpp v114, v114, v114 row_bcast:15 row_mask:0xa bank_mask:0xf
	v_add_f32_dpp v115, v115, v115 row_bcast:15 row_mask:0xa bank_mask:0xf
	v_add_f32_dpp v116, v116, v116 row_bcast:15 row_mask:0xa bank_mask:0xf
	v_add_f32_dpp v117, v117, v117 row_bcast:15 row_mask:0xa bank_mask:0xf
	v_add_f32_dpp v118, v118, v118 row_bcast:15 row_mask:0xa bank_mask:0xf
	v_add_f32_dpp v119, v119, v119 row_bcast:15 row_mask:0xa bank_mask:0xf
	v_add_f32_dpp v120, v120, v120 row_bcast:15 row_mask:0xa bank_mask:0xf
	v_add_f32_dpp v121, v121, v121 row_bcast:15 row_mask:0xa bank_mask:0xf
	v_add_f32_dpp v122, v122, v122 row_bcast:15 row_mask:0xa bank_mask:0xf
	v_add_f32_dpp v123, v123, v123 row_bcast:15 row_mask:0xa bank_mask:0xf
	v_add_f32_dpp v124, v124, v124 row_bcast:15 row_mask:0xa bank_mask:0xf
	v_add_f32_dpp v125, v125, v125 row_bcast:15 row_mask:0xa bank_mask:0xf
	v_add_f32_dpp v126, v126, v126 row_bcast:15 row_mask:0xa bank_mask:0xf
	v_add_f32_dpp v127, v127, v127 row_bcast:15 row_mask:0xa bank_mask:0xf
	v_add_f32_dpp v128, v128, v128 row_bcast:15 row_mask:0xa bank_mask:0xf
	v_add_f32_dpp v129, v129, v129 row_bcast:15 row_mask:0xa bank_mask:0xf
	v_add_f32_dpp v130, v130, v130 row_bcast:15 row_mask:0xa bank_mask:0xf
	v_add_f32_dpp v131, v131, v131 row_bcast:15 row_mask:0xa bank_mask:0xf
	v_add_f32_dpp v132, v132, v132 row_bcast:15 row_mask:0xa bank_mask:0xf
	v_add_f32_dpp v133, v133, v133 row_bcast:15 row_mask:0xa bank_mask:0xf
	v_add_f32_dpp v134, v134, v134 row_bcast:15 row_mask:0xa bank_mask:0xf
	v_add_f32_dpp v135, v135, v135 row_bcast:15 row_mask:0xa bank_mask:0xf
	v_add_f32_dpp v136, v136, v136 row_bcast:15 row_mask:0xa bank_mask:0xf
	v_add_f32_dpp v137, v137, v137 row_bcast:15 row_mask:0xa bank_mask:0xf
	v_add_f32_dpp v138, v138, v138 row_bcast:15 row_mask:0xa bank_mask:0xf
	v_add_f32_dpp v139, v139, v139 row_bcast:15 row_mask:0xa bank_mask:0xf
	v_add_f32_dpp v140, v140, v140 row_bcast:15 row_mask:0xa bank_mask:0xf
	v_add_f32_dpp v141, v141, v141 row_bcast:15 row_mask:0xa bank_mask:0xf
	v_add_f32_dpp v142, v142, v142 row_bcast:15 row_mask:0xa bank_mask:0xf
	v_add_f32_dpp v143, v143, v143 row_bcast:15 row_mask:0xa bank_mask:0xf
	v_add_f32_dpp v144, v144, v144 row_bcast:15 row_mask:0xa bank_mask:0xf
	v_add_f32_dpp v145, v145, v145 row_bcast:15 row_mask:0xa bank_mask:0xf
	v_add_f32_dpp v146, v146, v146 row_bcast:15 row_mask:0xa bank_mask:0xf
	v_add_f32_dpp v147, v147, v147 row_bcast:15 row_mask:0xa bank_mask:0xf
	v_add_f32_dpp v148, v148, v148 row_bcast:15 row_mask:0xa bank_mask:0xf
	v_add_f32_dpp v149, v149, v149 row_bcast:15 row_mask:0xa bank_mask:0xf
	v_add_f32_dpp v150, v150, v150 row_bcast:15 row_mask:0xa bank_mask:0xf
	v_add_f32_dpp v151, v151, v151 row_bcast:15 row_mask:0xa bank_mask:0xf
	v_add_f32_dpp v152, v152, v152 row_bcast:15 row_mask:0xa bank_mask:0xf
	v_add_f32_dpp v153, v153, v153 row_bcast:15 row_mask:0xa bank_mask:0xf
	v_add_f32_dpp v154, v154, v154 row_bcast:15 row_mask:0xa bank_mask:0xf
	v_add_f32_dpp v155, v155, v155 row_bcast:15 row_mask:0xa bank_mask:0xf
	v_add_f32_dpp v156, v156, v156 row_bcast:15 row_mask:0xa bank_mask:0xf
	v_add_f32_dpp v157, v157, v157 row_bcast:15 row_mask:0xa bank_mask:0xf
	v_add_f32_dpp v158, v158, v158 row_bcast:15 row_mask:0xa bank_mask:0xf
	v_add_f32_dpp v159, v159, v159 row_bcast:15 row_mask:0xa bank_mask:0xf
	v_add_f32_dpp v160, v160, v160 row_bcast:15 row_mask:0xa bank_mask:0xf
	v_add_f32_dpp v161, v161, v161 row_bcast:15 row_mask:0xa bank_mask:0xf
	v_add_f32_dpp v98, v98, v98 row_bcast:31 row_mask:0xc bank_mask:0xf
	v_add_f32_dpp v99, v99, v99 row_bcast:31 row_mask:0xc bank_mask:0xf
	v_add_f32_dpp v100, v100, v100 row_bcast:31 row_mask:0xc bank_mask:0xf
	v_add_f32_dpp v101, v101, v101 row_bcast:31 row_mask:0xc bank_mask:0xf
	v_add_f32_dpp v102, v102, v102 row_bcast:31 row_mask:0xc bank_mask:0xf
	v_add_f32_dpp v103, v103, v103 row_bcast:31 row_mask:0xc bank_mask:0xf
	v_add_f32_dpp v104, v104, v104 row_bcast:31 row_mask:0xc bank_mask:0xf
	v_add_f32_dpp v105, v105, v105 row_bcast:31 row_mask:0xc bank_mask:0xf
	v_add_f32_dpp v106, v106, v106 row_bcast:31 row_mask:0xc bank_mask:0xf
	v_add_f32_dpp v107, v107, v107 row_bcast:31 row_mask:0xc bank_mask:0xf
	v_add_f32_dpp v108, v108, v108 row_bcast:31 row_mask:0xc bank_mask:0xf
	v_add_f32_dpp v109, v109, v109 row_bcast:31 row_mask:0xc bank_mask:0xf
	v_add_f32_dpp v110, v110, v110 row_bcast:31 row_mask:0xc bank_mask:0xf
	v_add_f32_dpp v111, v111, v111 row_bcast:31 row_mask:0xc bank_mask:0xf
	v_add_f32_dpp v112, v112, v112 row_bcast:31 row_mask:0xc bank_mask:0xf
	v_add_f32_dpp v113, v113, v113 row_bcast:31 row_mask:0xc bank_mask:0xf
	v_add_f32_dpp v114, v114, v114 row_bcast:31 row_mask:0xc bank_mask:0xf
	v_add_f32_dpp v115, v115, v115 row_bcast:31 row_mask:0xc bank_mask:0xf
	v_add_f32_dpp v116, v116, v116 row_bcast:31 row_mask:0xc bank_mask:0xf
	v_add_f32_dpp v117, v117, v117 row_bcast:31 row_mask:0xc bank_mask:0xf
	v_add_f32_dpp v118, v118, v118 row_bcast:31 row_mask:0xc bank_mask:0xf
	v_add_f32_dpp v119, v119, v119 row_bcast:31 row_mask:0xc bank_mask:0xf
	v_add_f32_dpp v120, v120, v120 row_bcast:31 row_mask:0xc bank_mask:0xf
	v_add_f32_dpp v121, v121, v121 row_bcast:31 row_mask:0xc bank_mask:0xf
	v_add_f32_dpp v122, v122, v122 row_bcast:31 row_mask:0xc bank_mask:0xf
	v_add_f32_dpp v123, v123, v123 row_bcast:31 row_mask:0xc bank_mask:0xf
	v_add_f32_dpp v124, v124, v124 row_bcast:31 row_mask:0xc bank_mask:0xf
	v_add_f32_dpp v125, v125, v125 row_bcast:31 row_mask:0xc bank_mask:0xf
	v_add_f32_dpp v126, v126, v126 row_bcast:31 row_mask:0xc bank_mask:0xf
	v_add_f32_dpp v127, v127, v127 row_bcast:31 row_mask:0xc bank_mask:0xf
	v_add_f32_dpp v128, v128, v128 row_bcast:31 row_mask:0xc bank_mask:0xf
	v_add_f32_dpp v129, v129, v129 row_bcast:31 row_mask:0xc bank_mask:0xf
	v_add_f32_dpp v130, v130, v130 row_bcast:31 row_mask:0xc bank_mask:0xf
	v_add_f32_dpp v131, v131, v131 row_bcast:31 row_mask:0xc bank_mask:0xf
	v_add_f32_dpp v132, v132, v132 row_bcast:31 row_mask:0xc bank_mask:0xf
	v_add_f32_dpp v133, v133, v133 row_bcast:31 row_mask:0xc bank_mask:0xf
	v_add_f32_dpp v134, v134, v134 row_bcast:31 row_mask:0xc bank_mask:0xf
	v_add_f32_dpp v135, v135, v135 row_bcast:31 row_mask:0xc bank_mask:0xf
	v_add_f32_dpp v136, v136, v136 row_bcast:31 row_mask:0xc bank_mask:0xf
	v_add_f32_dpp v137, v137, v137 row_bcast:31 row_mask:0xc bank_mask:0xf
	v_add_f32_dpp v138, v138, v138 row_bcast:31 row_mask:0xc bank_mask:0xf
	v_add_f32_dpp v139, v139, v139 row_bcast:31 row_mask:0xc bank_mask:0xf
	v_add_f32_dpp v140, v140, v140 row_bcast:31 row_mask:0xc bank_mask:0xf
	v_add_f32_dpp v141, v141, v141 row_bcast:31 row_mask:0xc bank_mask:0xf
	v_add_f32_dpp v142, v142, v142 row_bcast:31 row_mask:0xc bank_mask:0xf
	v_add_f32_dpp v143, v143, v143 row_bcast:31 row_mask:0xc bank_mask:0xf
	v_add_f32_dpp v144, v144, v144 row_bcast:31 row_mask:0xc bank_mask:0xf
	v_add_f32_dpp v145, v145, v145 row_bcast:31 row_mask:0xc bank_mask:0xf
	v_add_f32_dpp v146, v146, v146 row_bcast:31 row_mask:0xc bank_mask:0xf
	v_add_f32_dpp v147, v147, v147 row_bcast:31 row_mask:0xc bank_mask:0xf
	v_add_f32_dpp v148, v148, v148 row_bcast:31 row_mask:0xc bank_mask:0xf
	v_add_f32_dpp v149, v149, v149 row_bcast:31 row_mask:0xc bank_mask:0xf
	v_add_f32_dpp v150, v150, v150 row_bcast:31 row_mask:0xc bank_mask:0xf
	v_add_f32_dpp v151, v151, v151 row_bcast:31 row_mask:0xc bank_mask:0xf
	v_add_f32_dpp v152, v152, v152 row_bcast:31 row_mask:0xc bank_mask:0xf
	v_add_f32_dpp v153, v153, v153 row_bcast:31 row_mask:0xc bank_mask:0xf
	v_add_f32_dpp v154, v154, v154 row_bcast:31 row_mask:0xc bank_mask:0xf
	v_add_f32_dpp v155, v155, v155 row_bcast:31 row_mask:0xc bank_mask:0xf
	v_add_f32_dpp v156, v156, v156 row_bcast:31 row_mask:0xc bank_mask:0xf
	v_add_f32_dpp v157, v157, v157 row_bcast:31 row_mask:0xc bank_mask:0xf
	v_add_f32_dpp v158, v158, v158 row_bcast:31 row_mask:0xc bank_mask:0xf
	v_add_f32_dpp v159, v159, v159 row_bcast:31 row_mask:0xc bank_mask:0xf
	v_add_f32_dpp v160, v160, v160 row_bcast:31 row_mask:0xc bank_mask:0xf
	v_add_f32_dpp v161, v161, v161 row_bcast:31 row_mask:0xc bank_mask:0xf
	s_nop 0
	v_readlane_b32 s40, v98, 63
	v_readlane_b32 s41, v99, 63
	v_readlane_b32 s46, v100, 63
	v_readlane_b32 s47, v101, 63
	v_readlane_b32 s51, v102, 63
	v_readlane_b32 s57, v103, 63
	v_readlane_b32 s58, v104, 63
	v_readlane_b32 s59, v105, 63
	v_readlane_b32 s60, v106, 63
	v_readlane_b32 s61, v107, 63
	v_readlane_b32 s62, v108, 63
	v_readlane_b32 s63, v109, 63
	v_readlane_b32 s70, v110, 63
	v_readlane_b32 s71, v111, 63
	v_readlane_b32 s74, v112, 63
	v_readlane_b32 s75, v113, 63
	s_nop 1
	v_writelane_b32 v12, s40, 0
	v_writelane_b32 v12, s41, 1
	v_writelane_b32 v12, s46, 2
	v_writelane_b32 v12, s47, 3
	v_writelane_b32 v12, s51, 4
	v_writelane_b32 v12, s57, 5
	v_writelane_b32 v12, s58, 6
	v_writelane_b32 v12, s59, 7
	v_writelane_b32 v12, s60, 8
	v_writelane_b32 v12, s61, 9
	v_writelane_b32 v12, s62, 10
	v_writelane_b32 v12, s63, 11
	v_writelane_b32 v12, s70, 12
	v_writelane_b32 v12, s71, 13
	v_writelane_b32 v12, s74, 14
	v_writelane_b32 v12, s75, 15
	v_readlane_b32 s40, v114, 63
	v_readlane_b32 s41, v115, 63
	v_readlane_b32 s46, v116, 63
	v_readlane_b32 s47, v117, 63
	v_readlane_b32 s51, v118, 63
	v_readlane_b32 s57, v119, 63
	v_readlane_b32 s58, v120, 63
	v_readlane_b32 s59, v121, 63
	v_readlane_b32 s60, v122, 63
	v_readlane_b32 s61, v123, 63
	v_readlane_b32 s62, v124, 63
	v_readlane_b32 s63, v125, 63
	v_readlane_b32 s70, v126, 63
	v_readlane_b32 s71, v127, 63
	v_readlane_b32 s74, v128, 63
	v_readlane_b32 s75, v129, 63
	s_nop 1
	v_writelane_b32 v12, s40, 16
	v_writelane_b32 v12, s41, 17
	v_writelane_b32 v12, s46, 18
	v_writelane_b32 v12, s47, 19
	v_writelane_b32 v12, s51, 20
	v_writelane_b32 v12, s57, 21
	v_writelane_b32 v12, s58, 22
	v_writelane_b32 v12, s59, 23
	v_writelane_b32 v12, s60, 24
	v_writelane_b32 v12, s61, 25
	v_writelane_b32 v12, s62, 26
	v_writelane_b32 v12, s63, 27
	v_writelane_b32 v12, s70, 28
	v_writelane_b32 v12, s71, 29
	v_writelane_b32 v12, s74, 30
	v_writelane_b32 v12, s75, 31
	v_readlane_b32 s40, v130, 63
	v_readlane_b32 s41, v131, 63
	v_readlane_b32 s46, v132, 63
	v_readlane_b32 s47, v133, 63
	v_readlane_b32 s51, v134, 63
	v_readlane_b32 s57, v135, 63
	v_readlane_b32 s58, v136, 63
	v_readlane_b32 s59, v137, 63
	v_readlane_b32 s60, v138, 63
	v_readlane_b32 s61, v139, 63
	v_readlane_b32 s62, v140, 63
	v_readlane_b32 s63, v141, 63
	v_readlane_b32 s70, v142, 63
	v_readlane_b32 s71, v143, 63
	v_readlane_b32 s74, v144, 63
	v_readlane_b32 s75, v145, 63
	s_nop 1
	v_writelane_b32 v12, s40, 32
	v_writelane_b32 v12, s41, 33
	v_writelane_b32 v12, s46, 34
	v_writelane_b32 v12, s47, 35
	v_writelane_b32 v12, s51, 36
	v_writelane_b32 v12, s57, 37
	v_writelane_b32 v12, s58, 38
	v_writelane_b32 v12, s59, 39
	v_writelane_b32 v12, s60, 40
	v_writelane_b32 v12, s61, 41
	v_writelane_b32 v12, s62, 42
	v_writelane_b32 v12, s63, 43
	v_writelane_b32 v12, s70, 44
	v_writelane_b32 v12, s71, 45
	v_writelane_b32 v12, s74, 46
	v_writelane_b32 v12, s75, 47
	v_readlane_b32 s40, v146, 63
	v_readlane_b32 s41, v147, 63
	v_readlane_b32 s46, v148, 63
	v_readlane_b32 s47, v149, 63
	v_readlane_b32 s51, v150, 63
	v_readlane_b32 s57, v151, 63
	v_readlane_b32 s58, v152, 63
	v_readlane_b32 s59, v153, 63
	v_readlane_b32 s60, v154, 63
	v_readlane_b32 s61, v155, 63
	v_readlane_b32 s62, v156, 63
	v_readlane_b32 s63, v157, 63
	v_readlane_b32 s70, v158, 63
	v_readlane_b32 s71, v159, 63
	v_readlane_b32 s74, v160, 63
	v_readlane_b32 s75, v161, 63
	s_nop 1
	v_writelane_b32 v12, s40, 48
	v_writelane_b32 v12, s41, 49
	v_writelane_b32 v12, s46, 50
	v_writelane_b32 v12, s47, 51
	v_writelane_b32 v12, s51, 52
	v_writelane_b32 v12, s57, 53
	v_writelane_b32 v12, s58, 54
	v_writelane_b32 v12, s59, 55
	v_writelane_b32 v12, s60, 56
	v_writelane_b32 v12, s61, 57
	v_writelane_b32 v12, s62, 58
	v_writelane_b32 v12, s63, 59
	v_writelane_b32 v12, s70, 60
	v_writelane_b32 v12, s71, 61
	v_writelane_b32 v12, s74, 62
	v_writelane_b32 v12, s75, 63
	v_lshrrev_b32_e32 v10, 2, v0
	v_and_b32_e32 v11, 3, v0
	v_mul_lo_u32 v10, v10, s23
	v_add3_u32 v15, v10, v11, s82
	v_lshlrev_b32_e32 v15, 2, v15
	s_add_u32 s8, s0, s22
	s_addc_u32 s9, s1, 0
	global_store_dword v15, v12, s[8:9] sc1
	s_cmp_eq_u32 s93, 1
	s_cbranch_scc0 .LBB0_477
	s_mov_b32 s93, 2
	s_branch .Lp1_norm
.Lcv7_idle:
	s_cmp_eq_u32 s93, 1
	s_cbranch_scc0 .Lcv8_idle_arr
	s_mov_b32 s93, 2
	s_branch .Lp1_norm
